# peeled first K-iteration in all 6 GEMM loops (first-touch MFMAs use C=0), accumulator zeroing movs removed
# speedup vs baseline: 1.0249x; 1.0028x over previous
.LBB0_376:
	v_mov_b64_e32 v[0:1], 0x680
	s_ashr_i32 s73, s72, 31
	v_cmp_lt_i64_e32 vcc, s[14:15], v[0:1]
	s_lshl_b64 s[14:15], s[72:73], 20
	s_add_u32 s76, s28, s14
	s_addc_u32 s77, s29, s15
	s_and_b64 s[14:15], vcc, exec
	s_cselect_b32 s14, s77, s13
	s_cselect_b32 s15, s76, s12
	s_ashr_i32 s75, s74, 31
	s_lshl_b64 s[46:47], s[74:75], 20
	s_add_u32 s78, s17, s46
	s_addc_u32 s79, s18, s47
	s_and_b64 s[46:47], vcc, exec
	s_cselect_b32 s67, s79, s81
	s_cselect_b32 s68, s78, s80
	s_add_u32 s46, s12, 0x80080
	s_addc_u32 s47, s13, 0
	s_add_u32 s12, s80, 0x100
	s_addc_u32 s13, s81, 0
	s_mov_b32 s73, -2
	s_waitcnt lgkmcnt(0)
	s_add_u32 s75, s46, 0xfff80080
	s_addc_u32 s80, s47, -1
	s_add_i32 s96, 0, 0x10000
	v_add_u32_e32 v76, s96, v239
	ds_read_b128 v[64:67], v76
	ds_read_b128 v[68:71], v76 offset:1024
	ds_read_b128 v[72:75], v76 offset:2048
	ds_read_b128 v[76:79], v76 offset:3072
	s_cmp_eq_u32 s73, 28
	s_cselect_b32 s83, s14, s80
	s_cselect_b32 s82, s15, s75
	s_cselect_b32 s81, s67, s13
	s_cselect_b32 s80, s68, s12
	ds_read_b128 v[80:83], v248
	ds_read_b128 v[84:87], v248 offset:1024
	ds_read_b128 v[88:91], v248 offset:2048
	ds_read_b128 v[92:95], v248 offset:3072
	ds_read_b128 v[184:187], v248 offset:4096
	ds_read_b128 v[188:191], v248 offset:5120
	ds_read_b128 v[192:195], v248 offset:6144
	ds_read_b128 v[196:199], v248 offset:7168
	s_waitcnt lgkmcnt(8)
	s_barrier
	s_waitcnt lgkmcnt(0)
	s_waitcnt lgkmcnt(0)
	v_mfma_f32_16x16x32_bf16 v[156:159], v[64:67], v[80:83], 0
	v_mfma_f32_16x16x32_bf16 v[152:155], v[72:75], v[80:83], 0
	v_mfma_f32_16x16x32_bf16 v[148:151], v[64:67], v[88:91], 0
	v_mfma_f32_16x16x32_bf16 v[140:143], v[72:75], v[88:91], 0
	v_mfma_f32_16x16x32_bf16 v[132:135], v[64:67], v[184:187], 0
	v_mfma_f32_16x16x32_bf16 v[124:127], v[72:75], v[184:187], 0
	v_mfma_f32_16x16x32_bf16 v[116:119], v[64:67], v[192:195], 0
	v_mfma_f32_16x16x32_bf16 v[108:111], v[72:75], v[192:195], 0
	v_mfma_f32_16x16x32_bf16 v[156:159], v[68:71], v[84:87], v[156:159]
	v_mfma_f32_16x16x32_bf16 v[152:155], v[76:79], v[84:87], v[152:155]
	v_mfma_f32_16x16x32_bf16 v[148:151], v[68:71], v[92:95], v[148:151]
	v_mfma_f32_16x16x32_bf16 v[140:143], v[76:79], v[92:95], v[140:143]
	v_mfma_f32_16x16x32_bf16 v[132:135], v[68:71], v[188:191], v[132:135]
	v_mfma_f32_16x16x32_bf16 v[124:127], v[76:79], v[188:191], v[124:127]
	v_mfma_f32_16x16x32_bf16 v[116:119], v[68:71], v[196:199], v[116:119]
	v_mfma_f32_16x16x32_bf16 v[108:111], v[76:79], v[196:199], v[108:111]
	s_barrier
	v_lshl_add_u64 v[200:201], s[46:47], 0, v[180:181]
	s_add_i32 m0, s20, 0xc000
	s_nop 0
	global_load_lds_dwordx4 v[200:201], off
	v_lshl_add_u64 v[200:201], s[46:47], 0, v[182:183]
	s_add_i32 m0, s20, 0xe000
	s_nop 0
	global_load_lds_dwordx4 v[200:201], off
	s_add_i32 s75, 0, 0x14000
	s_add_i32 s96, s96, s19
	v_add_u32_e32 v160, s75, v239
	v_lshl_add_u64 v[224:225], s[80:81], 0, v[174:175]
	s_mov_b32 m0, s96
	ds_read_b128 v[200:203], v160
	ds_read_b128 v[204:207], v160 offset:1024
	ds_read_b128 v[208:211], v160 offset:2048
	ds_read_b128 v[212:215], v160 offset:3072
	global_load_lds_dwordx4 v[224:225], off
	v_lshl_add_u64 v[226:227], s[80:81], 0, v[170:171]
	s_add_i32 m0, s96, 0x2000
	s_nop 0
	global_load_lds_dwordx4 v[226:227], off
	s_barrier
	s_waitcnt lgkmcnt(0)
	s_waitcnt lgkmcnt(0)
	v_mfma_f32_16x16x32_bf16 v[144:147], v[200:203], v[80:83], 0
	v_mfma_f32_16x16x32_bf16 v[80:83], v[208:211], v[80:83], 0
	v_mfma_f32_16x16x32_bf16 v[144:147], v[204:207], v[84:87], v[144:147]
	v_mfma_f32_16x16x32_bf16 v[80:83], v[212:215], v[84:87], v[80:83]
	v_mfma_f32_16x16x32_bf16 v[84:87], v[200:203], v[88:91], 0
	v_mfma_f32_16x16x32_bf16 v[88:91], v[208:211], v[88:91], 0
	v_mfma_f32_16x16x32_bf16 v[104:107], v[208:211], v[184:187], 0
	v_mfma_f32_16x16x32_bf16 v[100:103], v[200:203], v[192:195], 0
	v_mfma_f32_16x16x32_bf16 v[96:99], v[208:211], v[192:195], 0
	v_mfma_f32_16x16x32_bf16 v[84:87], v[204:207], v[92:95], v[84:87]
	v_mfma_f32_16x16x32_bf16 v[88:91], v[212:215], v[92:95], v[88:91]
	v_mfma_f32_16x16x32_bf16 v[92:95], v[200:203], v[184:187], 0
	v_mfma_f32_16x16x32_bf16 v[104:107], v[212:215], v[188:191], v[104:107]
	v_mfma_f32_16x16x32_bf16 v[100:103], v[204:207], v[196:199], v[100:103]
	v_mfma_f32_16x16x32_bf16 v[96:99], v[212:215], v[196:199], v[96:99]
	v_mfma_f32_16x16x32_bf16 v[92:95], v[204:207], v[188:191], v[92:95]
	s_mov_b32 m0, s20
	v_lshl_add_u64 v[228:229], s[82:83], 0, v[176:177]
	s_barrier
	ds_read_b128 v[112:115], v248 offset:16384
	ds_read_b128 v[120:123], v248 offset:17408
	ds_read_b128 v[128:131], v248 offset:18432
	ds_read_b128 v[136:139], v248 offset:19456
	ds_read_b128 v[184:187], v248 offset:20480
	ds_read_b128 v[188:191], v248 offset:21504
	ds_read_b128 v[192:195], v248 offset:22528
	ds_read_b128 v[196:199], v248 offset:23552
	global_load_lds_dwordx4 v[228:229], off
	v_lshl_add_u64 v[230:231], s[82:83], 0, v[172:173]
	s_mov_b32 m0, s21
	s_nop 0
	global_load_lds_dwordx4 v[230:231], off
	s_barrier
	s_waitcnt lgkmcnt(0)
	s_waitcnt lgkmcnt(0)
	v_mfma_f32_16x16x32_bf16 v[60:63], v[64:67], v[112:115], 0
	v_mfma_f32_16x16x32_bf16 v[56:59], v[72:75], v[112:115], 0
	v_mfma_f32_16x16x32_bf16 v[44:47], v[64:67], v[128:131], 0
	v_mfma_f32_16x16x32_bf16 v[40:43], v[72:75], v[128:131], 0
	v_mfma_f32_16x16x32_bf16 v[28:31], v[64:67], v[184:187], 0
	v_mfma_f32_16x16x32_bf16 v[24:27], v[72:75], v[184:187], 0
	v_mfma_f32_16x16x32_bf16 v[12:15], v[64:67], v[192:195], 0
	v_mfma_f32_16x16x32_bf16 v[8:11], v[72:75], v[192:195], 0
	v_mfma_f32_16x16x32_bf16 v[60:63], v[68:71], v[120:123], v[60:63]
	v_mfma_f32_16x16x32_bf16 v[56:59], v[76:79], v[120:123], v[56:59]
	v_mfma_f32_16x16x32_bf16 v[44:47], v[68:71], v[136:139], v[44:47]
	v_mfma_f32_16x16x32_bf16 v[40:43], v[76:79], v[136:139], v[40:43]
	v_mfma_f32_16x16x32_bf16 v[28:31], v[68:71], v[188:191], v[28:31]
	v_mfma_f32_16x16x32_bf16 v[24:27], v[76:79], v[188:191], v[24:27]
	v_mfma_f32_16x16x32_bf16 v[12:15], v[68:71], v[196:199], v[12:15]
	v_mfma_f32_16x16x32_bf16 v[8:11], v[76:79], v[196:199], v[8:11]
	s_barrier
	s_add_u32 s96, s80, 0x80000
	s_addc_u32 s97, s81, 0
	s_add_i32 s75, s75, s19
	v_lshl_add_u64 v[64:65], s[96:97], 0, v[174:175]
	s_mov_b32 m0, s75
	s_nop 0
	global_load_lds_dwordx4 v[64:65], off
	v_lshl_add_u64 v[64:65], s[96:97], 0, v[170:171]
	s_add_i32 m0, s75, 0x2000
	s_nop 0
	global_load_lds_dwordx4 v[64:65], off
	s_waitcnt vmcnt(6)
	s_barrier
	v_mfma_f32_16x16x32_bf16 v[52:55], v[200:203], v[112:115], 0
	v_mfma_f32_16x16x32_bf16 v[48:51], v[208:211], v[112:115], 0
	v_mfma_f32_16x16x32_bf16 v[36:39], v[200:203], v[128:131], 0
	v_mfma_f32_16x16x32_bf16 v[32:35], v[208:211], v[128:131], 0
	v_mfma_f32_16x16x32_bf16 v[20:23], v[200:203], v[184:187], 0
	v_mfma_f32_16x16x32_bf16 v[16:19], v[208:211], v[184:187], 0
	v_mfma_f32_16x16x32_bf16 v[4:7], v[200:203], v[192:195], 0
	v_mfma_f32_16x16x32_bf16 v[0:3], v[208:211], v[192:195], 0
	v_mfma_f32_16x16x32_bf16 v[52:55], v[204:207], v[120:123], v[52:55]
	v_mfma_f32_16x16x32_bf16 v[48:51], v[212:215], v[120:123], v[48:51]
	v_mfma_f32_16x16x32_bf16 v[36:39], v[204:207], v[136:139], v[36:39]
	v_mfma_f32_16x16x32_bf16 v[32:35], v[212:215], v[136:139], v[32:35]
	v_mfma_f32_16x16x32_bf16 v[20:23], v[204:207], v[188:191], v[20:23]
	v_mfma_f32_16x16x32_bf16 v[16:19], v[212:215], v[188:191], v[16:19]
	v_mfma_f32_16x16x32_bf16 v[4:7], v[204:207], v[196:199], v[4:7]
	v_mfma_f32_16x16x32_bf16 v[0:3], v[212:215], v[196:199], v[0:3]
	s_add_i32 s75, 0, 0x18000
	v_add_u32_e32 v76, s75, v239
	s_barrier
	ds_read_b128 v[64:67], v76
	ds_read_b128 v[68:71], v76 offset:1024
	ds_read_b128 v[72:75], v76 offset:2048
	ds_read_b128 v[76:79], v76 offset:3072
	ds_read_b128 v[112:115], v248 offset:32768
	ds_read_b128 v[120:123], v248 offset:33792
	ds_read_b128 v[184:187], v248 offset:34816
	ds_read_b128 v[188:191], v248 offset:35840
	ds_read_b128 v[192:195], v248 offset:36864
	ds_read_b128 v[196:199], v248 offset:37888
	ds_read_b128 v[200:203], v248 offset:38912
	ds_read_b128 v[204:207], v248 offset:39936
	s_waitcnt lgkmcnt(8)
	s_barrier
	s_waitcnt lgkmcnt(0)
	s_waitcnt lgkmcnt(0)
	v_mfma_f32_16x16x32_bf16 v[128:131], v[64:67], v[112:115], v[156:159]
	v_mfma_f32_16x16x32_bf16 v[156:159], v[68:71], v[120:123], v[128:131]
	v_mfma_f32_16x16x32_bf16 v[128:131], v[72:75], v[112:115], v[152:155]
	v_mfma_f32_16x16x32_bf16 v[152:155], v[76:79], v[120:123], v[128:131]
	v_mfma_f32_16x16x32_bf16 v[128:131], v[64:67], v[184:187], v[148:151]
	v_mfma_f32_16x16x32_bf16 v[148:151], v[68:71], v[188:191], v[128:131]
	v_mfma_f32_16x16x32_bf16 v[128:131], v[72:75], v[184:187], v[140:143]
	v_mfma_f32_16x16x32_bf16 v[140:143], v[76:79], v[188:191], v[128:131]
	v_mfma_f32_16x16x32_bf16 v[128:131], v[64:67], v[192:195], v[132:135]
	v_mfma_f32_16x16x32_bf16 v[124:127], v[72:75], v[192:195], v[124:127]
	v_mfma_f32_16x16x32_bf16 v[116:119], v[64:67], v[200:203], v[116:119]
	v_mfma_f32_16x16x32_bf16 v[108:111], v[72:75], v[200:203], v[108:111]
	v_mfma_f32_16x16x32_bf16 v[132:135], v[68:71], v[196:199], v[128:131]
	v_mfma_f32_16x16x32_bf16 v[124:127], v[76:79], v[196:199], v[124:127]
	v_mfma_f32_16x16x32_bf16 v[116:119], v[68:71], v[204:207], v[116:119]
	v_mfma_f32_16x16x32_bf16 v[108:111], v[76:79], v[204:207], v[108:111]
	s_barrier
	s_add_u32 s82, s82, 0x80000
	s_addc_u32 s83, s83, 0
	v_lshl_add_u64 v[128:129], s[82:83], 0, v[176:177]
	s_mov_b32 m0, s22
	s_nop 0
	global_load_lds_dwordx4 v[128:129], off
	v_lshl_add_u64 v[128:129], s[82:83], 0, v[172:173]
	s_mov_b32 m0, s23
	s_nop 0
	global_load_lds_dwordx4 v[128:129], off
	s_add_i32 s82, 0, 0x1c000
	v_add_u32_e32 v128, s82, v239
	s_add_i32 s75, s75, s19
	ds_read_b128 v[208:211], v128
	ds_read_b128 v[212:215], v128 offset:1024
	ds_read_b128 v[216:219], v128 offset:2048
	ds_read_b128 v[220:223], v128 offset:3072
	v_lshl_add_u64 v[128:129], v[224:225], 0, s[92:93]
	s_mov_b32 m0, s75
	s_nop 0
	global_load_lds_dwordx4 v[128:129], off
	v_lshl_add_u64 v[128:129], v[226:227], 0, s[92:93]
	s_add_i32 m0, s75, 0x2000
	s_nop 0
	global_load_lds_dwordx4 v[128:129], off
	s_barrier
	s_waitcnt lgkmcnt(0)
	s_waitcnt lgkmcnt(0)
	v_mfma_f32_16x16x32_bf16 v[80:83], v[216:219], v[112:115], v[80:83]
	v_mfma_f32_16x16x32_bf16 v[128:131], v[208:211], v[112:115], v[144:147]
	v_mfma_f32_16x16x32_bf16 v[136:139], v[220:223], v[120:123], v[80:83]
	v_mfma_f32_16x16x32_bf16 v[80:83], v[208:211], v[184:187], v[84:87]
	v_mfma_f32_16x16x32_bf16 v[144:147], v[212:215], v[120:123], v[128:131]
	v_mfma_f32_16x16x32_bf16 v[128:131], v[212:215], v[188:191], v[80:83]
	v_mfma_f32_16x16x32_bf16 v[80:83], v[216:219], v[184:187], v[88:91]
	v_mfma_f32_16x16x32_bf16 v[120:123], v[220:223], v[188:191], v[80:83]
	v_mfma_f32_16x16x32_bf16 v[80:83], v[208:211], v[192:195], v[92:95]
	v_mfma_f32_16x16x32_bf16 v[112:115], v[212:215], v[196:199], v[80:83]
	v_mfma_f32_16x16x32_bf16 v[80:83], v[216:219], v[192:195], v[104:107]
	v_mfma_f32_16x16x32_bf16 v[104:107], v[220:223], v[196:199], v[80:83]
	v_mfma_f32_16x16x32_bf16 v[80:83], v[208:211], v[200:203], v[100:103]
	v_mfma_f32_16x16x32_bf16 v[100:103], v[212:215], v[204:207], v[80:83]
	v_mfma_f32_16x16x32_bf16 v[80:83], v[216:219], v[200:203], v[96:99]
	v_mfma_f32_16x16x32_bf16 v[96:99], v[220:223], v[204:207], v[80:83]
	s_mov_b32 m0, s25
	v_lshl_add_u64 v[200:201], v[228:229], 0, s[92:93]
	s_barrier
	s_nop 2
	ds_read_b128 v[80:83], v248 offset:49152
	ds_read_b128 v[84:87], v248 offset:50176
	ds_read_b128 v[88:91], v248 offset:51200
	ds_read_b128 v[92:95], v248 offset:52224
	ds_read_b128 v[184:187], v248 offset:53248
	ds_read_b128 v[188:191], v248 offset:54272
	ds_read_b128 v[192:195], v248 offset:55296
	ds_read_b128 v[196:199], v248 offset:56320
	global_load_lds_dwordx4 v[200:201], off
	v_lshl_add_u64 v[200:201], v[230:231], 0, s[92:93]
	s_mov_b32 m0, s26
	s_nop 0
	global_load_lds_dwordx4 v[200:201], off
	s_barrier
	s_waitcnt lgkmcnt(0)
	s_waitcnt lgkmcnt(0)
	v_mfma_f32_16x16x32_bf16 v[60:63], v[64:67], v[80:83], v[60:63]
	v_mfma_f32_16x16x32_bf16 v[56:59], v[72:75], v[80:83], v[56:59]
	v_mfma_f32_16x16x32_bf16 v[44:47], v[64:67], v[88:91], v[44:47]
	v_mfma_f32_16x16x32_bf16 v[40:43], v[72:75], v[88:91], v[40:43]
	v_mfma_f32_16x16x32_bf16 v[28:31], v[64:67], v[184:187], v[28:31]
	v_mfma_f32_16x16x32_bf16 v[24:27], v[72:75], v[184:187], v[24:27]
	v_mfma_f32_16x16x32_bf16 v[12:15], v[64:67], v[192:195], v[12:15]
	v_mfma_f32_16x16x32_bf16 v[8:11], v[72:75], v[192:195], v[8:11]
	v_mfma_f32_16x16x32_bf16 v[60:63], v[68:71], v[84:87], v[60:63]
	v_mfma_f32_16x16x32_bf16 v[56:59], v[76:79], v[84:87], v[56:59]
	v_mfma_f32_16x16x32_bf16 v[44:47], v[68:71], v[92:95], v[44:47]
	v_mfma_f32_16x16x32_bf16 v[40:43], v[76:79], v[92:95], v[40:43]
	v_mfma_f32_16x16x32_bf16 v[28:31], v[68:71], v[188:191], v[28:31]
	v_mfma_f32_16x16x32_bf16 v[24:27], v[76:79], v[188:191], v[24:27]
	v_mfma_f32_16x16x32_bf16 v[12:15], v[68:71], v[196:199], v[12:15]
	v_mfma_f32_16x16x32_bf16 v[8:11], v[76:79], v[196:199], v[8:11]
	s_barrier
	s_add_u32 s80, s80, 0x80080
	s_addc_u32 s81, s81, 0
	s_add_i32 s75, s82, s19
	v_lshl_add_u64 v[64:65], s[80:81], 0, v[174:175]
	s_mov_b32 m0, s75
	s_nop 0
	global_load_lds_dwordx4 v[64:65], off
	v_lshl_add_u64 v[64:65], s[80:81], 0, v[170:171]
	s_add_i32 m0, s75, 0x2000
	s_nop 0
	global_load_lds_dwordx4 v[64:65], off
	s_waitcnt vmcnt(6)
	s_barrier
	v_mfma_f32_16x16x32_bf16 v[52:55], v[208:211], v[80:83], v[52:55]
	v_mfma_f32_16x16x32_bf16 v[48:51], v[216:219], v[80:83], v[48:51]
	v_mfma_f32_16x16x32_bf16 v[36:39], v[208:211], v[88:91], v[36:39]
	v_mfma_f32_16x16x32_bf16 v[32:35], v[216:219], v[88:91], v[32:35]
	v_mfma_f32_16x16x32_bf16 v[20:23], v[208:211], v[184:187], v[20:23]
	v_mfma_f32_16x16x32_bf16 v[16:19], v[216:219], v[184:187], v[16:19]
	v_mfma_f32_16x16x32_bf16 v[4:7], v[208:211], v[192:195], v[4:7]
	v_mfma_f32_16x16x32_bf16 v[0:3], v[216:219], v[192:195], v[0:3]
	v_mfma_f32_16x16x32_bf16 v[52:55], v[212:215], v[84:87], v[52:55]
	v_mfma_f32_16x16x32_bf16 v[48:51], v[220:223], v[84:87], v[48:51]
	v_mfma_f32_16x16x32_bf16 v[36:39], v[212:215], v[92:95], v[36:39]
	v_mfma_f32_16x16x32_bf16 v[32:35], v[220:223], v[92:95], v[32:35]
	v_mfma_f32_16x16x32_bf16 v[20:23], v[212:215], v[188:191], v[20:23]
	v_mfma_f32_16x16x32_bf16 v[16:19], v[220:223], v[188:191], v[16:19]
	v_mfma_f32_16x16x32_bf16 v[4:7], v[212:215], v[196:199], v[4:7]
	v_mfma_f32_16x16x32_bf16 v[0:3], v[220:223], v[196:199], v[0:3]
	s_add_i32 s73, s73, 2
	s_add_u32 s46, s46, 0x100
	s_addc_u32 s47, s47, 0
	s_add_u32 s12, s12, 0x100
	s_addc_u32 s13, s13, 0
	s_cmp_gt_u32 s73, 29
	s_barrier

.LBB0_473:
	v_mov_b64_e32 v[0:1], 0x300
	s_ashr_i32 s5, s4, 31
	v_cmp_lt_i64_e32 vcc, s[12:13], v[0:1]
	s_lshl_b64 s[12:13], s[4:5], 18
	s_add_u32 s50, s36, s12
	s_addc_u32 s51, s58, s13
	s_and_b64 s[12:13], vcc, exec
	s_cselect_b32 s5, s51, s73
	s_cselect_b32 s12, s50, s72
	s_ashr_i32 s47, s46, 31
	s_lshl_b64 s[66:67], s[46:47], 18
	s_add_u32 s70, s15, s66
	s_addc_u32 s71, s16, s67
	s_and_b64 s[66:67], vcc, exec
	s_cselect_b32 s13, s71, s75
	s_cselect_b32 s45, s70, s74
	s_add_u32 s72, s72, 0x20080
	s_addc_u32 s73, s73, 0
	s_add_u32 s47, s74, 0x100
	s_addc_u32 s66, s75, 0
	s_mov_b32 s67, -2
	s_add_u32 s68, s72, 0xfffe0080
	s_addc_u32 s74, s73, -1
	s_add_i32 s78, 0, 0x10000
	v_add_u32_e32 v140, s78, v173
	ds_read_b128 v[128:131], v140
	ds_read_b128 v[132:135], v140 offset:1024
	ds_read_b128 v[136:139], v140 offset:2048
	ds_read_b128 v[140:143], v140 offset:3072
	s_cmp_eq_u32 s67, 4
	s_cselect_b32 s77, s5, s74
	s_cselect_b32 s76, s12, s68
	s_cselect_b32 s75, s13, s66
	s_cselect_b32 s74, s45, s47
	ds_read_b128 v[174:177], v185
	ds_read_b128 v[180:183], v185 offset:1024
	ds_read_b128 v[186:189], v185 offset:2048
	ds_read_b128 v[190:193], v185 offset:3072
	ds_read_b128 v[194:197], v185 offset:4096
	ds_read_b128 v[198:201], v185 offset:5120
	ds_read_b128 v[202:205], v185 offset:6144
	ds_read_b128 v[206:209], v185 offset:7168
	s_waitcnt lgkmcnt(8)
	s_barrier
	s_waitcnt lgkmcnt(0)
	s_waitcnt lgkmcnt(0)
	v_mfma_f32_16x16x32_bf16 v[124:127], v[128:131], v[174:177], 0
	v_mfma_f32_16x16x32_bf16 v[120:123], v[136:139], v[174:177], 0
	v_mfma_f32_16x16x32_bf16 v[112:115], v[128:131], v[186:189], 0
	v_mfma_f32_16x16x32_bf16 v[104:107], v[136:139], v[186:189], 0
	v_mfma_f32_16x16x32_bf16 v[96:99], v[128:131], v[194:197], 0
	v_mfma_f32_16x16x32_bf16 v[88:91], v[136:139], v[194:197], 0
	v_mfma_f32_16x16x32_bf16 v[80:83], v[128:131], v[202:205], 0
	v_mfma_f32_16x16x32_bf16 v[72:75], v[136:139], v[202:205], 0
	v_mfma_f32_16x16x32_bf16 v[124:127], v[132:135], v[180:183], v[124:127]
	v_mfma_f32_16x16x32_bf16 v[120:123], v[140:143], v[180:183], v[120:123]
	v_mfma_f32_16x16x32_bf16 v[112:115], v[132:135], v[190:193], v[112:115]
	v_mfma_f32_16x16x32_bf16 v[104:107], v[140:143], v[190:193], v[104:107]
	v_mfma_f32_16x16x32_bf16 v[96:99], v[132:135], v[198:201], v[96:99]
	v_mfma_f32_16x16x32_bf16 v[88:91], v[140:143], v[198:201], v[88:91]
	v_mfma_f32_16x16x32_bf16 v[80:83], v[132:135], v[206:209], v[80:83]
	v_mfma_f32_16x16x32_bf16 v[72:75], v[140:143], v[206:209], v[72:75]
	s_barrier
	v_lshl_add_u64 v[158:159], s[72:73], 0, v[154:155]
	s_add_i32 m0, s18, 0xc000
	s_nop 0
	global_load_lds_dwordx4 v[158:159], off
	v_lshl_add_u64 v[158:159], s[72:73], 0, v[156:157]
	s_add_i32 m0, s18, 0xe000
	s_nop 0
	global_load_lds_dwordx4 v[158:159], off
	s_add_i32 s68, 0, 0x14000
	v_add_u32_e32 v158, s68, v173
	s_add_i32 s78, s78, s17
	ds_read_b128 v[210:213], v158
	ds_read_b128 v[214:217], v158 offset:1024
	ds_read_b128 v[218:221], v158 offset:2048
	ds_read_b128 v[222:225], v158 offset:3072
	v_lshl_add_u64 v[158:159], s[74:75], 0, v[148:149]
	s_mov_b32 m0, s78
	v_lshl_add_u64 v[170:171], s[74:75], 0, v[144:145]
	global_load_lds_dwordx4 v[158:159], off
	s_add_i32 m0, s78, 0x2000
	s_nop 0
	global_load_lds_dwordx4 v[170:171], off
	s_barrier
	s_waitcnt lgkmcnt(0)
	s_waitcnt lgkmcnt(0)
	v_mfma_f32_16x16x32_bf16 v[116:119], v[210:213], v[174:177], 0
	v_mfma_f32_16x16x32_bf16 v[108:111], v[218:221], v[174:177], 0
	v_mfma_f32_16x16x32_bf16 v[100:103], v[210:213], v[186:189], 0
	v_mfma_f32_16x16x32_bf16 v[92:95], v[218:221], v[186:189], 0
	v_mfma_f32_16x16x32_bf16 v[84:87], v[210:213], v[194:197], 0
	v_mfma_f32_16x16x32_bf16 v[76:79], v[218:221], v[194:197], 0
	v_mfma_f32_16x16x32_bf16 v[68:71], v[210:213], v[202:205], 0
	v_mfma_f32_16x16x32_bf16 v[64:67], v[218:221], v[202:205], 0
	v_mfma_f32_16x16x32_bf16 v[116:119], v[214:217], v[180:183], v[116:119]
	v_mfma_f32_16x16x32_bf16 v[108:111], v[222:225], v[180:183], v[108:111]
	v_mfma_f32_16x16x32_bf16 v[100:103], v[214:217], v[190:193], v[100:103]
	v_mfma_f32_16x16x32_bf16 v[92:95], v[222:225], v[190:193], v[92:95]
	v_mfma_f32_16x16x32_bf16 v[84:87], v[214:217], v[198:201], v[84:87]
	v_mfma_f32_16x16x32_bf16 v[76:79], v[222:225], v[198:201], v[76:79]
	v_mfma_f32_16x16x32_bf16 v[68:71], v[214:217], v[206:209], v[68:71]
	v_mfma_f32_16x16x32_bf16 v[64:67], v[222:225], v[206:209], v[64:67]
	s_mov_b32 m0, s18
	v_lshl_add_u64 v[226:227], s[76:77], 0, v[150:151]
	s_barrier
	ds_read_b128 v[174:177], v185 offset:16384
	ds_read_b128 v[180:183], v185 offset:17408
	ds_read_b128 v[186:189], v185 offset:18432
	ds_read_b128 v[190:193], v185 offset:19456
	ds_read_b128 v[194:197], v185 offset:20480
	ds_read_b128 v[198:201], v185 offset:21504
	ds_read_b128 v[202:205], v185 offset:22528
	ds_read_b128 v[206:209], v185 offset:23552
	global_load_lds_dwordx4 v[226:227], off
	v_lshl_add_u64 v[228:229], s[76:77], 0, v[146:147]
	s_mov_b32 m0, s19
	s_nop 0
	global_load_lds_dwordx4 v[228:229], off
	s_barrier
	s_waitcnt lgkmcnt(0)
	s_waitcnt lgkmcnt(0)
	v_mfma_f32_16x16x32_bf16 v[60:63], v[128:131], v[174:177], 0
	v_mfma_f32_16x16x32_bf16 v[56:59], v[136:139], v[174:177], 0
	v_mfma_f32_16x16x32_bf16 v[48:51], v[128:131], v[186:189], 0
	v_mfma_f32_16x16x32_bf16 v[40:43], v[136:139], v[186:189], 0
	v_mfma_f32_16x16x32_bf16 v[32:35], v[128:131], v[194:197], 0
	v_mfma_f32_16x16x32_bf16 v[24:27], v[136:139], v[194:197], 0
	v_mfma_f32_16x16x32_bf16 v[16:19], v[128:131], v[202:205], 0
	v_mfma_f32_16x16x32_bf16 v[8:11], v[136:139], v[202:205], 0
	v_mfma_f32_16x16x32_bf16 v[60:63], v[132:135], v[180:183], v[60:63]
	v_mfma_f32_16x16x32_bf16 v[56:59], v[140:143], v[180:183], v[56:59]
	v_mfma_f32_16x16x32_bf16 v[48:51], v[132:135], v[190:193], v[48:51]
	v_mfma_f32_16x16x32_bf16 v[40:43], v[140:143], v[190:193], v[40:43]
	v_mfma_f32_16x16x32_bf16 v[32:35], v[132:135], v[198:201], v[32:35]
	v_mfma_f32_16x16x32_bf16 v[24:27], v[140:143], v[198:201], v[24:27]
	v_mfma_f32_16x16x32_bf16 v[16:19], v[132:135], v[206:209], v[16:19]
	v_mfma_f32_16x16x32_bf16 v[8:11], v[140:143], v[206:209], v[8:11]
	s_barrier
	s_add_u32 s78, s74, 0x20000
	s_addc_u32 s79, s75, 0
	s_add_i32 s68, s68, s17
	v_lshl_add_u64 v[128:129], s[78:79], 0, v[148:149]
	s_mov_b32 m0, s68
	s_nop 0
	global_load_lds_dwordx4 v[128:129], off
	v_lshl_add_u64 v[128:129], s[78:79], 0, v[144:145]
	s_add_i32 m0, s68, 0x2000
	s_nop 0
	global_load_lds_dwordx4 v[128:129], off
	s_waitcnt vmcnt(6)
	s_barrier
	v_mfma_f32_16x16x32_bf16 v[52:55], v[210:213], v[174:177], 0
	v_mfma_f32_16x16x32_bf16 v[44:47], v[218:221], v[174:177], 0
	v_mfma_f32_16x16x32_bf16 v[36:39], v[210:213], v[186:189], 0
	v_mfma_f32_16x16x32_bf16 v[28:31], v[218:221], v[186:189], 0
	v_mfma_f32_16x16x32_bf16 v[20:23], v[210:213], v[194:197], 0
	v_mfma_f32_16x16x32_bf16 v[12:15], v[218:221], v[194:197], 0
	v_mfma_f32_16x16x32_bf16 v[4:7], v[210:213], v[202:205], 0
	v_mfma_f32_16x16x32_bf16 v[0:3], v[218:221], v[202:205], 0
	v_mfma_f32_16x16x32_bf16 v[52:55], v[214:217], v[180:183], v[52:55]
	v_mfma_f32_16x16x32_bf16 v[44:47], v[222:225], v[180:183], v[44:47]
	v_mfma_f32_16x16x32_bf16 v[36:39], v[214:217], v[190:193], v[36:39]
	v_mfma_f32_16x16x32_bf16 v[28:31], v[222:225], v[190:193], v[28:31]
	v_mfma_f32_16x16x32_bf16 v[20:23], v[214:217], v[198:201], v[20:23]
	v_mfma_f32_16x16x32_bf16 v[12:15], v[222:225], v[198:201], v[12:15]
	v_mfma_f32_16x16x32_bf16 v[4:7], v[214:217], v[206:209], v[4:7]
	v_mfma_f32_16x16x32_bf16 v[0:3], v[222:225], v[206:209], v[0:3]
	s_add_i32 s68, 0, 0x18000
	v_add_u32_e32 v140, s68, v173
	s_barrier
	ds_read_b128 v[128:131], v140
	ds_read_b128 v[132:135], v140 offset:1024
	ds_read_b128 v[136:139], v140 offset:2048
	ds_read_b128 v[140:143], v140 offset:3072
	ds_read_b128 v[174:177], v185 offset:32768
	ds_read_b128 v[180:183], v185 offset:33792
	ds_read_b128 v[186:189], v185 offset:34816
	ds_read_b128 v[190:193], v185 offset:35840
	ds_read_b128 v[194:197], v185 offset:36864
	ds_read_b128 v[198:201], v185 offset:37888
	ds_read_b128 v[202:205], v185 offset:38912
	ds_read_b128 v[206:209], v185 offset:39936
	s_waitcnt lgkmcnt(8)
	s_barrier
	s_waitcnt lgkmcnt(0)
	s_waitcnt lgkmcnt(0)
	v_mfma_f32_16x16x32_bf16 v[124:127], v[128:131], v[174:177], v[124:127]
	v_mfma_f32_16x16x32_bf16 v[120:123], v[136:139], v[174:177], v[120:123]
	v_mfma_f32_16x16x32_bf16 v[112:115], v[128:131], v[186:189], v[112:115]
	v_mfma_f32_16x16x32_bf16 v[104:107], v[136:139], v[186:189], v[104:107]
	v_mfma_f32_16x16x32_bf16 v[96:99], v[128:131], v[194:197], v[96:99]
	v_mfma_f32_16x16x32_bf16 v[88:91], v[136:139], v[194:197], v[88:91]
	v_mfma_f32_16x16x32_bf16 v[80:83], v[128:131], v[202:205], v[80:83]
	v_mfma_f32_16x16x32_bf16 v[72:75], v[136:139], v[202:205], v[72:75]
	v_mfma_f32_16x16x32_bf16 v[124:127], v[132:135], v[180:183], v[124:127]
	v_mfma_f32_16x16x32_bf16 v[120:123], v[140:143], v[180:183], v[120:123]
	v_mfma_f32_16x16x32_bf16 v[112:115], v[132:135], v[190:193], v[112:115]
	v_mfma_f32_16x16x32_bf16 v[104:107], v[140:143], v[190:193], v[104:107]
	v_mfma_f32_16x16x32_bf16 v[96:99], v[132:135], v[198:201], v[96:99]
	v_mfma_f32_16x16x32_bf16 v[88:91], v[140:143], v[198:201], v[88:91]
	v_mfma_f32_16x16x32_bf16 v[80:83], v[132:135], v[206:209], v[80:83]
	v_mfma_f32_16x16x32_bf16 v[72:75], v[140:143], v[206:209], v[72:75]
	s_barrier
	s_add_u32 s76, s76, 0x20000
	s_addc_u32 s77, s77, 0
	v_lshl_add_u64 v[210:211], s[76:77], 0, v[150:151]
	s_mov_b32 m0, s20
	s_nop 0
	global_load_lds_dwordx4 v[210:211], off
	v_lshl_add_u64 v[210:211], s[76:77], 0, v[146:147]
	s_mov_b32 m0, s21
	s_nop 0
	global_load_lds_dwordx4 v[210:211], off
	s_add_i32 s76, 0, 0x1c000
	s_add_i32 s68, s68, s17
	v_add_u32_e32 v160, s76, v173
	v_lshl_add_u64 v[158:159], v[158:159], 0, s[92:93]
	s_mov_b32 m0, s68
	ds_read_b128 v[210:213], v160
	ds_read_b128 v[214:217], v160 offset:1024
	ds_read_b128 v[218:221], v160 offset:2048
	ds_read_b128 v[222:225], v160 offset:3072
	global_load_lds_dwordx4 v[158:159], off
	v_lshl_add_u64 v[158:159], v[170:171], 0, s[92:93]
	s_add_i32 m0, s68, 0x2000
	s_nop 0
	global_load_lds_dwordx4 v[158:159], off
	s_barrier
	s_waitcnt lgkmcnt(0)
	s_waitcnt lgkmcnt(0)
	v_mfma_f32_16x16x32_bf16 v[116:119], v[210:213], v[174:177], v[116:119]
	v_mfma_f32_16x16x32_bf16 v[108:111], v[218:221], v[174:177], v[108:111]
	v_mfma_f32_16x16x32_bf16 v[100:103], v[210:213], v[186:189], v[100:103]
	v_mfma_f32_16x16x32_bf16 v[92:95], v[218:221], v[186:189], v[92:95]
	v_mfma_f32_16x16x32_bf16 v[84:87], v[210:213], v[194:197], v[84:87]
	v_mfma_f32_16x16x32_bf16 v[76:79], v[218:221], v[194:197], v[76:79]
	v_mfma_f32_16x16x32_bf16 v[68:71], v[210:213], v[202:205], v[68:71]
	v_mfma_f32_16x16x32_bf16 v[64:67], v[218:221], v[202:205], v[64:67]
	v_mfma_f32_16x16x32_bf16 v[116:119], v[214:217], v[180:183], v[116:119]
	v_mfma_f32_16x16x32_bf16 v[108:111], v[222:225], v[180:183], v[108:111]
	v_mfma_f32_16x16x32_bf16 v[100:103], v[214:217], v[190:193], v[100:103]
	v_mfma_f32_16x16x32_bf16 v[92:95], v[222:225], v[190:193], v[92:95]
	v_mfma_f32_16x16x32_bf16 v[84:87], v[214:217], v[198:201], v[84:87]
	v_mfma_f32_16x16x32_bf16 v[76:79], v[222:225], v[198:201], v[76:79]
	v_mfma_f32_16x16x32_bf16 v[68:71], v[214:217], v[206:209], v[68:71]
	v_mfma_f32_16x16x32_bf16 v[64:67], v[222:225], v[206:209], v[64:67]
	s_mov_b32 m0, s22
	v_lshl_add_u64 v[158:159], v[226:227], 0, s[92:93]
	s_barrier
	ds_read_b128 v[174:177], v185 offset:49152
	ds_read_b128 v[180:183], v185 offset:50176
	ds_read_b128 v[186:189], v185 offset:51200
	ds_read_b128 v[190:193], v185 offset:52224
	ds_read_b128 v[194:197], v185 offset:53248
	ds_read_b128 v[198:201], v185 offset:54272
	ds_read_b128 v[202:205], v185 offset:55296
	ds_read_b128 v[206:209], v185 offset:56320
	global_load_lds_dwordx4 v[158:159], off
	v_lshl_add_u64 v[158:159], v[228:229], 0, s[92:93]
	s_mov_b32 m0, s23
	s_nop 0
	global_load_lds_dwordx4 v[158:159], off
	s_barrier
	s_waitcnt lgkmcnt(0)
	s_waitcnt lgkmcnt(0)
	v_mfma_f32_16x16x32_bf16 v[60:63], v[128:131], v[174:177], v[60:63]
	v_mfma_f32_16x16x32_bf16 v[56:59], v[136:139], v[174:177], v[56:59]
	v_mfma_f32_16x16x32_bf16 v[48:51], v[128:131], v[186:189], v[48:51]
	v_mfma_f32_16x16x32_bf16 v[40:43], v[136:139], v[186:189], v[40:43]
	v_mfma_f32_16x16x32_bf16 v[32:35], v[128:131], v[194:197], v[32:35]
	v_mfma_f32_16x16x32_bf16 v[24:27], v[136:139], v[194:197], v[24:27]
	v_mfma_f32_16x16x32_bf16 v[16:19], v[128:131], v[202:205], v[16:19]
	v_mfma_f32_16x16x32_bf16 v[8:11], v[136:139], v[202:205], v[8:11]
	v_mfma_f32_16x16x32_bf16 v[60:63], v[132:135], v[180:183], v[60:63]
	v_mfma_f32_16x16x32_bf16 v[56:59], v[140:143], v[180:183], v[56:59]
	v_mfma_f32_16x16x32_bf16 v[48:51], v[132:135], v[190:193], v[48:51]
	v_mfma_f32_16x16x32_bf16 v[40:43], v[140:143], v[190:193], v[40:43]
	v_mfma_f32_16x16x32_bf16 v[32:35], v[132:135], v[198:201], v[32:35]
	v_mfma_f32_16x16x32_bf16 v[24:27], v[140:143], v[198:201], v[24:27]
	v_mfma_f32_16x16x32_bf16 v[16:19], v[132:135], v[206:209], v[16:19]
	v_mfma_f32_16x16x32_bf16 v[8:11], v[140:143], v[206:209], v[8:11]
	s_barrier
	s_add_u32 s74, s74, 0x20080
	s_addc_u32 s75, s75, 0
	s_add_i32 s68, s76, s17
	v_lshl_add_u64 v[128:129], s[74:75], 0, v[148:149]
	s_mov_b32 m0, s68
	s_nop 0
	global_load_lds_dwordx4 v[128:129], off
	v_lshl_add_u64 v[128:129], s[74:75], 0, v[144:145]
	s_add_i32 m0, s68, 0x2000
	s_nop 0
	global_load_lds_dwordx4 v[128:129], off
	s_waitcnt vmcnt(6)
	s_barrier
	v_mfma_f32_16x16x32_bf16 v[52:55], v[210:213], v[174:177], v[52:55]
	v_mfma_f32_16x16x32_bf16 v[44:47], v[218:221], v[174:177], v[44:47]
	v_mfma_f32_16x16x32_bf16 v[36:39], v[210:213], v[186:189], v[36:39]
	v_mfma_f32_16x16x32_bf16 v[28:31], v[218:221], v[186:189], v[28:31]
	v_mfma_f32_16x16x32_bf16 v[20:23], v[210:213], v[194:197], v[20:23]
	v_mfma_f32_16x16x32_bf16 v[12:15], v[218:221], v[194:197], v[12:15]
	v_mfma_f32_16x16x32_bf16 v[4:7], v[210:213], v[202:205], v[4:7]
	v_mfma_f32_16x16x32_bf16 v[0:3], v[218:221], v[202:205], v[0:3]
	v_mfma_f32_16x16x32_bf16 v[52:55], v[214:217], v[180:183], v[52:55]
	v_mfma_f32_16x16x32_bf16 v[44:47], v[222:225], v[180:183], v[44:47]
	v_mfma_f32_16x16x32_bf16 v[36:39], v[214:217], v[190:193], v[36:39]
	v_mfma_f32_16x16x32_bf16 v[28:31], v[222:225], v[190:193], v[28:31]
	v_mfma_f32_16x16x32_bf16 v[20:23], v[214:217], v[198:201], v[20:23]
	v_mfma_f32_16x16x32_bf16 v[12:15], v[222:225], v[198:201], v[12:15]
	v_mfma_f32_16x16x32_bf16 v[4:7], v[214:217], v[206:209], v[4:7]
	v_mfma_f32_16x16x32_bf16 v[0:3], v[222:225], v[206:209], v[0:3]
	s_add_i32 s67, s67, 2
	s_add_u32 s72, s72, 0x100
	s_addc_u32 s73, s73, 0
	s_add_u32 s47, s47, 0x100
	s_addc_u32 s66, s66, 0
	s_cmp_gt_u32 s67, 5
	s_barrier

.LBB0_492:
	s_ashr_i32 s47, s46, 31
	v_cmp_lt_i64_e32 vcc, s[12:13], v[164:165]
	s_lshl_b64 s[12:13], s[46:47], 18
	s_add_u32 s72, s38, s12
	s_addc_u32 s73, s69, s13
	s_and_b64 s[12:13], vcc, exec
	s_cselect_b32 s12, s73, s77
	s_cselect_b32 s13, s72, s76
	s_ashr_i32 s71, s70, 31
	s_lshl_b64 s[14:15], s[70:71], 18
	s_add_u32 s74, s17, s14
	s_addc_u32 s75, s18, s15
	s_and_b64 s[14:15], vcc, exec
	s_cselect_b32 s14, s75, s1
	s_cselect_b32 s15, s74, s0
	s_add_u32 s76, s76, 0x20080
	s_addc_u32 s77, s77, 0
	s_add_u32 s47, s0, 0x100
	s_addc_u32 s66, s1, 0
	s_mov_b32 s67, -2
	s_add_u32 s0, s76, 0xfffe0080
	s_addc_u32 s1, s77, -1
	s_add_i32 s68, 0, 0x10000
	v_add_u32_e32 v146, s68, v153
	ds_read_b128 v[128:131], v146
	ds_read_b128 v[132:135], v146 offset:1024
	ds_read_b128 v[154:157], v146 offset:2048
	ds_read_b128 v[170:173], v146 offset:3072
	s_cmp_eq_u32 s67, 4
	s_cselect_b32 s79, s12, s1
	s_cselect_b32 s78, s13, s0
	s_cselect_b32 s1, s14, s66
	s_cselect_b32 s0, s15, s47
	ds_read_b128 v[178:181], v177
	ds_read_b128 v[182:185], v177 offset:1024
	ds_read_b128 v[186:189], v177 offset:2048
	ds_read_b128 v[190:193], v177 offset:3072
	ds_read_b128 v[194:197], v177 offset:4096
	ds_read_b128 v[198:201], v177 offset:5120
	ds_read_b128 v[202:205], v177 offset:6144
	ds_read_b128 v[206:209], v177 offset:7168
	s_waitcnt lgkmcnt(8)
	s_barrier
	s_waitcnt lgkmcnt(0)
	s_waitcnt lgkmcnt(0)
	v_mfma_f32_16x16x32_bf16 v[124:127], v[128:131], v[178:181], 0
	v_mfma_f32_16x16x32_bf16 v[120:123], v[154:157], v[178:181], 0
	v_mfma_f32_16x16x32_bf16 v[112:115], v[128:131], v[186:189], 0
	v_mfma_f32_16x16x32_bf16 v[104:107], v[154:157], v[186:189], 0
	v_mfma_f32_16x16x32_bf16 v[96:99], v[128:131], v[194:197], 0
	v_mfma_f32_16x16x32_bf16 v[88:91], v[154:157], v[194:197], 0
	v_mfma_f32_16x16x32_bf16 v[80:83], v[128:131], v[202:205], 0
	v_mfma_f32_16x16x32_bf16 v[72:75], v[154:157], v[202:205], 0
	v_mfma_f32_16x16x32_bf16 v[124:127], v[132:135], v[182:185], v[124:127]
	v_mfma_f32_16x16x32_bf16 v[120:123], v[170:173], v[182:185], v[120:123]
	v_mfma_f32_16x16x32_bf16 v[112:115], v[132:135], v[190:193], v[112:115]
	v_mfma_f32_16x16x32_bf16 v[104:107], v[170:173], v[190:193], v[104:107]
	v_mfma_f32_16x16x32_bf16 v[96:99], v[132:135], v[198:201], v[96:99]
	v_mfma_f32_16x16x32_bf16 v[88:91], v[170:173], v[198:201], v[88:91]
	v_mfma_f32_16x16x32_bf16 v[80:83], v[132:135], v[206:209], v[80:83]
	v_mfma_f32_16x16x32_bf16 v[72:75], v[170:173], v[206:209], v[72:75]
	s_barrier
	v_lshl_add_u64 v[146:147], s[76:77], 0, v[142:143]
	s_add_i32 m0, s20, 0xc000
	s_nop 0
	global_load_lds_dwordx4 v[146:147], off
	v_lshl_add_u64 v[146:147], s[76:77], 0, v[144:145]
	s_add_i32 m0, s20, 0xe000
	s_nop 0
	global_load_lds_dwordx4 v[146:147], off
	s_add_i32 s71, 0, 0x14000
	v_add_u32_e32 v146, s71, v153
	s_add_i32 s68, s68, s19
	ds_read_b128 v[210:213], v146
	ds_read_b128 v[214:217], v146 offset:1024
	ds_read_b128 v[218:221], v146 offset:2048
	ds_read_b128 v[222:225], v146 offset:3072
	v_lshl_add_u64 v[146:147], s[0:1], 0, v[160:161]
	s_mov_b32 m0, s68
	v_lshl_add_u64 v[150:151], s[0:1], 0, v[136:137]
	global_load_lds_dwordx4 v[146:147], off
	s_add_i32 m0, s68, 0x2000
	s_nop 0
	global_load_lds_dwordx4 v[150:151], off
	s_barrier
	s_waitcnt lgkmcnt(0)
	s_waitcnt lgkmcnt(0)
	v_mfma_f32_16x16x32_bf16 v[116:119], v[210:213], v[178:181], 0
	v_mfma_f32_16x16x32_bf16 v[108:111], v[218:221], v[178:181], 0
	v_mfma_f32_16x16x32_bf16 v[100:103], v[210:213], v[186:189], 0
	v_mfma_f32_16x16x32_bf16 v[92:95], v[218:221], v[186:189], 0
	v_mfma_f32_16x16x32_bf16 v[84:87], v[210:213], v[194:197], 0
	v_mfma_f32_16x16x32_bf16 v[76:79], v[218:221], v[194:197], 0
	v_mfma_f32_16x16x32_bf16 v[68:71], v[210:213], v[202:205], 0
	v_mfma_f32_16x16x32_bf16 v[64:67], v[218:221], v[202:205], 0
	v_mfma_f32_16x16x32_bf16 v[116:119], v[214:217], v[182:185], v[116:119]
	v_mfma_f32_16x16x32_bf16 v[108:111], v[222:225], v[182:185], v[108:111]
	v_mfma_f32_16x16x32_bf16 v[100:103], v[214:217], v[190:193], v[100:103]
	v_mfma_f32_16x16x32_bf16 v[92:95], v[222:225], v[190:193], v[92:95]
	v_mfma_f32_16x16x32_bf16 v[84:87], v[214:217], v[198:201], v[84:87]
	v_mfma_f32_16x16x32_bf16 v[76:79], v[222:225], v[198:201], v[76:79]
	v_mfma_f32_16x16x32_bf16 v[68:71], v[214:217], v[206:209], v[68:71]
	v_mfma_f32_16x16x32_bf16 v[64:67], v[222:225], v[206:209], v[64:67]
	s_mov_b32 m0, s20
	v_lshl_add_u64 v[174:175], s[78:79], 0, v[140:141]
	s_barrier
	ds_read_b128 v[178:181], v177 offset:16384
	ds_read_b128 v[182:185], v177 offset:17408
	ds_read_b128 v[186:189], v177 offset:18432
	ds_read_b128 v[190:193], v177 offset:19456
	ds_read_b128 v[194:197], v177 offset:20480
	ds_read_b128 v[198:201], v177 offset:21504
	ds_read_b128 v[202:205], v177 offset:22528
	ds_read_b128 v[206:209], v177 offset:23552
	global_load_lds_dwordx4 v[174:175], off
	v_lshl_add_u64 v[226:227], s[78:79], 0, v[138:139]
	s_mov_b32 m0, s21
	s_nop 0
	global_load_lds_dwordx4 v[226:227], off
	s_barrier
	s_waitcnt lgkmcnt(0)
	s_waitcnt lgkmcnt(0)
	v_mfma_f32_16x16x32_bf16 v[60:63], v[128:131], v[178:181], 0
	v_mfma_f32_16x16x32_bf16 v[56:59], v[154:157], v[178:181], 0
	v_mfma_f32_16x16x32_bf16 v[48:51], v[128:131], v[186:189], 0
	v_mfma_f32_16x16x32_bf16 v[40:43], v[154:157], v[186:189], 0
	v_mfma_f32_16x16x32_bf16 v[32:35], v[128:131], v[194:197], 0
	v_mfma_f32_16x16x32_bf16 v[24:27], v[154:157], v[194:197], 0
	v_mfma_f32_16x16x32_bf16 v[16:19], v[128:131], v[202:205], 0
	v_mfma_f32_16x16x32_bf16 v[8:11], v[154:157], v[202:205], 0
	v_mfma_f32_16x16x32_bf16 v[60:63], v[132:135], v[182:185], v[60:63]
	v_mfma_f32_16x16x32_bf16 v[56:59], v[170:173], v[182:185], v[56:59]
	v_mfma_f32_16x16x32_bf16 v[48:51], v[132:135], v[190:193], v[48:51]
	v_mfma_f32_16x16x32_bf16 v[40:43], v[170:173], v[190:193], v[40:43]
	v_mfma_f32_16x16x32_bf16 v[32:35], v[132:135], v[198:201], v[32:35]
	v_mfma_f32_16x16x32_bf16 v[24:27], v[170:173], v[198:201], v[24:27]
	v_mfma_f32_16x16x32_bf16 v[16:19], v[132:135], v[206:209], v[16:19]
	v_mfma_f32_16x16x32_bf16 v[8:11], v[170:173], v[206:209], v[8:11]
	s_barrier
	s_add_u32 s80, s0, 0x20000
	s_addc_u32 s81, s1, 0
	s_add_i32 s68, s71, s19
	v_lshl_add_u64 v[128:129], s[80:81], 0, v[160:161]
	s_mov_b32 m0, s68
	s_nop 0
	global_load_lds_dwordx4 v[128:129], off
	v_lshl_add_u64 v[128:129], s[80:81], 0, v[136:137]
	s_add_i32 m0, s68, 0x2000
	s_nop 0
	global_load_lds_dwordx4 v[128:129], off
	s_waitcnt vmcnt(6)
	s_barrier
	v_mfma_f32_16x16x32_bf16 v[52:55], v[210:213], v[178:181], 0
	v_mfma_f32_16x16x32_bf16 v[44:47], v[218:221], v[178:181], 0
	v_mfma_f32_16x16x32_bf16 v[36:39], v[210:213], v[186:189], 0
	v_mfma_f32_16x16x32_bf16 v[28:31], v[218:221], v[186:189], 0
	v_mfma_f32_16x16x32_bf16 v[20:23], v[210:213], v[194:197], 0
	v_mfma_f32_16x16x32_bf16 v[12:15], v[218:221], v[194:197], 0
	v_mfma_f32_16x16x32_bf16 v[4:7], v[210:213], v[202:205], 0
	v_mfma_f32_16x16x32_bf16 v[0:3], v[218:221], v[202:205], 0
	v_mfma_f32_16x16x32_bf16 v[52:55], v[214:217], v[182:185], v[52:55]
	v_mfma_f32_16x16x32_bf16 v[44:47], v[222:225], v[182:185], v[44:47]
	v_mfma_f32_16x16x32_bf16 v[36:39], v[214:217], v[190:193], v[36:39]
	v_mfma_f32_16x16x32_bf16 v[28:31], v[222:225], v[190:193], v[28:31]
	v_mfma_f32_16x16x32_bf16 v[20:23], v[214:217], v[198:201], v[20:23]
	v_mfma_f32_16x16x32_bf16 v[12:15], v[222:225], v[198:201], v[12:15]
	v_mfma_f32_16x16x32_bf16 v[4:7], v[214:217], v[206:209], v[4:7]
	v_mfma_f32_16x16x32_bf16 v[0:3], v[222:225], v[206:209], v[0:3]
	s_add_i32 s68, 0, 0x18000
	v_add_u32_e32 v148, s68, v153
	s_barrier
	ds_read_b128 v[128:131], v148
	ds_read_b128 v[132:135], v148 offset:1024
	ds_read_b128 v[154:157], v148 offset:2048
	ds_read_b128 v[170:173], v148 offset:3072
	ds_read_b128 v[178:181], v177 offset:32768
	ds_read_b128 v[182:185], v177 offset:33792
	ds_read_b128 v[186:189], v177 offset:34816
	ds_read_b128 v[190:193], v177 offset:35840
	ds_read_b128 v[194:197], v177 offset:36864
	ds_read_b128 v[198:201], v177 offset:37888
	ds_read_b128 v[202:205], v177 offset:38912
	ds_read_b128 v[206:209], v177 offset:39936
	s_waitcnt lgkmcnt(8)
	s_barrier
	s_waitcnt lgkmcnt(0)
	s_waitcnt lgkmcnt(0)
	v_mfma_f32_16x16x32_bf16 v[124:127], v[128:131], v[178:181], v[124:127]
	v_mfma_f32_16x16x32_bf16 v[120:123], v[154:157], v[178:181], v[120:123]
	v_mfma_f32_16x16x32_bf16 v[112:115], v[128:131], v[186:189], v[112:115]
	v_mfma_f32_16x16x32_bf16 v[104:107], v[154:157], v[186:189], v[104:107]
	v_mfma_f32_16x16x32_bf16 v[96:99], v[128:131], v[194:197], v[96:99]
	v_mfma_f32_16x16x32_bf16 v[88:91], v[154:157], v[194:197], v[88:91]
	v_mfma_f32_16x16x32_bf16 v[80:83], v[128:131], v[202:205], v[80:83]
	v_mfma_f32_16x16x32_bf16 v[72:75], v[154:157], v[202:205], v[72:75]
	v_mfma_f32_16x16x32_bf16 v[124:127], v[132:135], v[182:185], v[124:127]
	v_mfma_f32_16x16x32_bf16 v[120:123], v[170:173], v[182:185], v[120:123]
	v_mfma_f32_16x16x32_bf16 v[112:115], v[132:135], v[190:193], v[112:115]
	v_mfma_f32_16x16x32_bf16 v[104:107], v[170:173], v[190:193], v[104:107]
	v_mfma_f32_16x16x32_bf16 v[96:99], v[132:135], v[198:201], v[96:99]
	v_mfma_f32_16x16x32_bf16 v[88:91], v[170:173], v[198:201], v[88:91]
	v_mfma_f32_16x16x32_bf16 v[80:83], v[132:135], v[206:209], v[80:83]
	v_mfma_f32_16x16x32_bf16 v[72:75], v[170:173], v[206:209], v[72:75]
	s_barrier
	s_add_u32 s78, s78, 0x20000
	s_addc_u32 s79, s79, 0
	v_lshl_add_u64 v[210:211], s[78:79], 0, v[140:141]
	s_mov_b32 m0, s22
	s_nop 0
	global_load_lds_dwordx4 v[210:211], off
	v_lshl_add_u64 v[210:211], s[78:79], 0, v[138:139]
	s_mov_b32 m0, s23
	s_nop 0
	global_load_lds_dwordx4 v[210:211], off
	s_add_i32 s71, 0, 0x1c000
	s_add_i32 s68, s68, s19
	v_add_u32_e32 v148, s71, v153
	v_lshl_add_u64 v[146:147], v[146:147], 0, s[92:93]
	s_mov_b32 m0, s68
	ds_read_b128 v[210:213], v148
	ds_read_b128 v[214:217], v148 offset:1024
	ds_read_b128 v[218:221], v148 offset:2048
	ds_read_b128 v[222:225], v148 offset:3072
	global_load_lds_dwordx4 v[146:147], off
	v_lshl_add_u64 v[146:147], v[150:151], 0, s[92:93]
	s_add_i32 m0, s68, 0x2000
	s_nop 0
	global_load_lds_dwordx4 v[146:147], off
	s_barrier
	s_waitcnt lgkmcnt(0)
	s_waitcnt lgkmcnt(0)
	v_mfma_f32_16x16x32_bf16 v[116:119], v[210:213], v[178:181], v[116:119]
	v_mfma_f32_16x16x32_bf16 v[108:111], v[218:221], v[178:181], v[108:111]
	v_mfma_f32_16x16x32_bf16 v[100:103], v[210:213], v[186:189], v[100:103]
	v_mfma_f32_16x16x32_bf16 v[92:95], v[218:221], v[186:189], v[92:95]
	v_mfma_f32_16x16x32_bf16 v[84:87], v[210:213], v[194:197], v[84:87]
	v_mfma_f32_16x16x32_bf16 v[76:79], v[218:221], v[194:197], v[76:79]
	v_mfma_f32_16x16x32_bf16 v[68:71], v[210:213], v[202:205], v[68:71]
	v_mfma_f32_16x16x32_bf16 v[64:67], v[218:221], v[202:205], v[64:67]
	v_mfma_f32_16x16x32_bf16 v[116:119], v[214:217], v[182:185], v[116:119]
	v_mfma_f32_16x16x32_bf16 v[108:111], v[222:225], v[182:185], v[108:111]
	v_mfma_f32_16x16x32_bf16 v[100:103], v[214:217], v[190:193], v[100:103]
	v_mfma_f32_16x16x32_bf16 v[92:95], v[222:225], v[190:193], v[92:95]
	v_mfma_f32_16x16x32_bf16 v[84:87], v[214:217], v[198:201], v[84:87]
	v_mfma_f32_16x16x32_bf16 v[76:79], v[222:225], v[198:201], v[76:79]
	v_mfma_f32_16x16x32_bf16 v[68:71], v[214:217], v[206:209], v[68:71]
	v_mfma_f32_16x16x32_bf16 v[64:67], v[222:225], v[206:209], v[64:67]
	s_mov_b32 m0, s24
	v_lshl_add_u64 v[146:147], v[174:175], 0, s[92:93]
	s_barrier
	ds_read_b128 v[178:181], v177 offset:49152
	ds_read_b128 v[182:185], v177 offset:50176
	ds_read_b128 v[186:189], v177 offset:51200
	ds_read_b128 v[190:193], v177 offset:52224
	ds_read_b128 v[194:197], v177 offset:53248
	ds_read_b128 v[198:201], v177 offset:54272
	ds_read_b128 v[202:205], v177 offset:55296
	ds_read_b128 v[206:209], v177 offset:56320
	global_load_lds_dwordx4 v[146:147], off
	v_lshl_add_u64 v[146:147], v[226:227], 0, s[92:93]
	s_mov_b32 m0, s25
	s_nop 0
	global_load_lds_dwordx4 v[146:147], off
	s_barrier
	s_waitcnt lgkmcnt(0)
	s_waitcnt lgkmcnt(0)
	v_mfma_f32_16x16x32_bf16 v[60:63], v[128:131], v[178:181], v[60:63]
	v_mfma_f32_16x16x32_bf16 v[56:59], v[154:157], v[178:181], v[56:59]
	v_mfma_f32_16x16x32_bf16 v[48:51], v[128:131], v[186:189], v[48:51]
	v_mfma_f32_16x16x32_bf16 v[40:43], v[154:157], v[186:189], v[40:43]
	v_mfma_f32_16x16x32_bf16 v[32:35], v[128:131], v[194:197], v[32:35]
	v_mfma_f32_16x16x32_bf16 v[24:27], v[154:157], v[194:197], v[24:27]
	v_mfma_f32_16x16x32_bf16 v[16:19], v[128:131], v[202:205], v[16:19]
	v_mfma_f32_16x16x32_bf16 v[8:11], v[154:157], v[202:205], v[8:11]
	v_mfma_f32_16x16x32_bf16 v[60:63], v[132:135], v[182:185], v[60:63]
	v_mfma_f32_16x16x32_bf16 v[56:59], v[170:173], v[182:185], v[56:59]
	v_mfma_f32_16x16x32_bf16 v[48:51], v[132:135], v[190:193], v[48:51]
	v_mfma_f32_16x16x32_bf16 v[40:43], v[170:173], v[190:193], v[40:43]
	v_mfma_f32_16x16x32_bf16 v[32:35], v[132:135], v[198:201], v[32:35]
	v_mfma_f32_16x16x32_bf16 v[24:27], v[170:173], v[198:201], v[24:27]
	v_mfma_f32_16x16x32_bf16 v[16:19], v[132:135], v[206:209], v[16:19]
	v_mfma_f32_16x16x32_bf16 v[8:11], v[170:173], v[206:209], v[8:11]
	s_barrier
	s_add_u32 s0, s0, 0x20080
	s_addc_u32 s1, s1, 0
	s_add_i32 s68, s71, s19
	v_lshl_add_u64 v[128:129], s[0:1], 0, v[160:161]
	s_mov_b32 m0, s68
	s_nop 0
	global_load_lds_dwordx4 v[128:129], off
	v_lshl_add_u64 v[128:129], s[0:1], 0, v[136:137]
	s_add_i32 m0, s68, 0x2000
	s_nop 0
	global_load_lds_dwordx4 v[128:129], off
	s_waitcnt vmcnt(6)
	s_barrier
	v_mfma_f32_16x16x32_bf16 v[52:55], v[210:213], v[178:181], v[52:55]
	v_mfma_f32_16x16x32_bf16 v[44:47], v[218:221], v[178:181], v[44:47]
	v_mfma_f32_16x16x32_bf16 v[36:39], v[210:213], v[186:189], v[36:39]
	v_mfma_f32_16x16x32_bf16 v[28:31], v[218:221], v[186:189], v[28:31]
	v_mfma_f32_16x16x32_bf16 v[20:23], v[210:213], v[194:197], v[20:23]
	v_mfma_f32_16x16x32_bf16 v[12:15], v[218:221], v[194:197], v[12:15]
	v_mfma_f32_16x16x32_bf16 v[4:7], v[210:213], v[202:205], v[4:7]
	v_mfma_f32_16x16x32_bf16 v[0:3], v[218:221], v[202:205], v[0:3]
	v_mfma_f32_16x16x32_bf16 v[52:55], v[214:217], v[182:185], v[52:55]
	v_mfma_f32_16x16x32_bf16 v[44:47], v[222:225], v[182:185], v[44:47]
	v_mfma_f32_16x16x32_bf16 v[36:39], v[214:217], v[190:193], v[36:39]
	v_mfma_f32_16x16x32_bf16 v[28:31], v[222:225], v[190:193], v[28:31]
	v_mfma_f32_16x16x32_bf16 v[20:23], v[214:217], v[198:201], v[20:23]
	v_mfma_f32_16x16x32_bf16 v[12:15], v[222:225], v[198:201], v[12:15]
	v_mfma_f32_16x16x32_bf16 v[4:7], v[214:217], v[206:209], v[4:7]
	v_mfma_f32_16x16x32_bf16 v[0:3], v[222:225], v[206:209], v[0:3]
	s_add_i32 s67, s67, 2
	s_add_u32 s76, s76, 0x100
	s_addc_u32 s77, s77, 0
	s_add_u32 s47, s47, 0x100
	s_addc_u32 s66, s66, 0
	s_cmp_gt_u32 s67, 5
	s_barrier

.LBB0_858:
	s_ashr_i32 s73, s72, 31
	v_cmp_lt_i64_e32 vcc, s[12:13], v[164:165]
	s_lshl_b64 s[12:13], s[72:73], 20
	s_add_u32 s76, s56, s12
	s_addc_u32 s77, s57, s13
	s_and_b64 s[12:13], vcc, exec
	s_cselect_b32 s12, s77, s9
	s_cselect_b32 s13, s76, s8
	s_ashr_i32 s75, s74, 31
	s_lshl_b64 s[14:15], s[74:75], 20
	s_add_u32 s78, s17, s14
	s_addc_u32 s79, s18, s15
	s_and_b64 s[14:15], vcc, exec
	s_cselect_b32 s14, s79, s1
	s_cselect_b32 s15, s78, s0
	s_add_u32 s8, s8, 0x80080
	s_addc_u32 s9, s9, 0
	s_add_u32 s48, s0, 0x100
	s_addc_u32 s49, s1, 0
	s_mov_b32 s50, -2
	s_add_u32 s0, s8, 0xfff80080
	s_addc_u32 s1, s9, -1
	s_add_i32 s51, 0, 0x10000
	v_add_u32_e32 v60, s51, v249
	ds_read_b128 v[48:51], v60
	ds_read_b128 v[52:55], v60 offset:1024
	ds_read_b128 v[56:59], v60 offset:2048
	ds_read_b128 v[60:63], v60 offset:3072
	s_cmp_eq_u32 s50, 28
	s_cselect_b32 s81, s12, s1
	s_cselect_b32 s80, s13, s0
	s_cselect_b32 s1, s14, s49
	s_cselect_b32 s0, s15, s48
	ds_read_b128 v[64:67], v251
	ds_read_b128 v[68:71], v251 offset:1024
	ds_read_b128 v[72:75], v251 offset:2048
	ds_read_b128 v[76:79], v251 offset:3072
	ds_read_b128 v[176:179], v251 offset:4096
	ds_read_b128 v[180:183], v251 offset:5120
	ds_read_b128 v[184:187], v251 offset:6144
	ds_read_b128 v[188:191], v251 offset:7168
	s_waitcnt lgkmcnt(8)
	s_barrier
	s_waitcnt lgkmcnt(0)
	s_waitcnt lgkmcnt(0)
	v_mfma_f32_16x16x32_bf16 v[156:159], v[48:51], v[64:67], 0
	v_mfma_f32_16x16x32_bf16 v[152:155], v[56:59], v[64:67], 0
	v_mfma_f32_16x16x32_bf16 v[140:143], v[48:51], v[72:75], 0
	v_mfma_f32_16x16x32_bf16 v[136:139], v[56:59], v[72:75], 0
	v_mfma_f32_16x16x32_bf16 v[124:127], v[48:51], v[176:179], 0
	v_mfma_f32_16x16x32_bf16 v[120:123], v[56:59], v[176:179], 0
	v_mfma_f32_16x16x32_bf16 v[108:111], v[48:51], v[184:187], 0
	v_mfma_f32_16x16x32_bf16 v[104:107], v[56:59], v[184:187], 0
	v_mfma_f32_16x16x32_bf16 v[156:159], v[52:55], v[68:71], v[156:159]
	v_mfma_f32_16x16x32_bf16 v[152:155], v[60:63], v[68:71], v[152:155]
	v_mfma_f32_16x16x32_bf16 v[140:143], v[52:55], v[76:79], v[140:143]
	v_mfma_f32_16x16x32_bf16 v[136:139], v[60:63], v[76:79], v[136:139]
	v_mfma_f32_16x16x32_bf16 v[124:127], v[52:55], v[180:183], v[124:127]
	v_mfma_f32_16x16x32_bf16 v[120:123], v[60:63], v[180:183], v[120:123]
	v_mfma_f32_16x16x32_bf16 v[108:111], v[52:55], v[188:191], v[108:111]
	v_mfma_f32_16x16x32_bf16 v[104:107], v[60:63], v[188:191], v[104:107]
	s_barrier
	v_lshl_add_u64 v[192:193], s[8:9], 0, v[172:173]
	s_add_i32 m0, s20, 0xc000
	s_nop 0
	global_load_lds_dwordx4 v[192:193], off
	v_lshl_add_u64 v[192:193], s[8:9], 0, v[174:175]
	s_add_i32 m0, s20, 0xe000
	s_nop 0
	global_load_lds_dwordx4 v[192:193], off
	s_add_i32 s68, 0, 0x14000
	s_add_i32 s51, s51, s19
	v_add_u32_e32 v204, s68, v249
	v_lshl_add_u64 v[216:217], s[0:1], 0, v[160:161]
	s_mov_b32 m0, s51
	ds_read_b128 v[192:195], v204
	ds_read_b128 v[196:199], v204 offset:1024
	ds_read_b128 v[200:203], v204 offset:2048
	ds_read_b128 v[204:207], v204 offset:3072
	global_load_lds_dwordx4 v[216:217], off
	v_lshl_add_u64 v[218:219], s[0:1], 0, v[170:171]
	s_add_i32 m0, s51, 0x2000
	s_nop 0
	global_load_lds_dwordx4 v[218:219], off
	s_barrier
	s_waitcnt lgkmcnt(0)
	s_waitcnt lgkmcnt(0)
	v_mfma_f32_16x16x32_bf16 v[148:151], v[192:195], v[64:67], 0
	v_mfma_f32_16x16x32_bf16 v[64:67], v[200:203], v[64:67], 0
	v_mfma_f32_16x16x32_bf16 v[148:151], v[196:199], v[68:71], v[148:151]
	v_mfma_f32_16x16x32_bf16 v[64:67], v[204:207], v[68:71], v[64:67]
	v_mfma_f32_16x16x32_bf16 v[68:71], v[192:195], v[72:75], 0
	v_mfma_f32_16x16x32_bf16 v[72:75], v[200:203], v[72:75], 0
	v_mfma_f32_16x16x32_bf16 v[112:115], v[200:203], v[176:179], 0
	v_mfma_f32_16x16x32_bf16 v[100:103], v[192:195], v[184:187], 0
	v_mfma_f32_16x16x32_bf16 v[96:99], v[200:203], v[184:187], 0
	v_mfma_f32_16x16x32_bf16 v[68:71], v[196:199], v[76:79], v[68:71]
	v_mfma_f32_16x16x32_bf16 v[72:75], v[204:207], v[76:79], v[72:75]
	v_mfma_f32_16x16x32_bf16 v[76:79], v[192:195], v[176:179], 0
	v_mfma_f32_16x16x32_bf16 v[112:115], v[204:207], v[180:183], v[112:115]
	v_mfma_f32_16x16x32_bf16 v[100:103], v[196:199], v[188:191], v[100:103]
	v_mfma_f32_16x16x32_bf16 v[96:99], v[204:207], v[188:191], v[96:99]
	v_mfma_f32_16x16x32_bf16 v[76:79], v[196:199], v[180:183], v[76:79]
	s_mov_b32 m0, s20
	v_lshl_add_u64 v[220:221], s[80:81], 0, v[160:161]
	s_barrier
	ds_read_b128 v[116:119], v251 offset:16384
	ds_read_b128 v[128:131], v251 offset:17408
	ds_read_b128 v[132:135], v251 offset:18432
	ds_read_b128 v[144:147], v251 offset:19456
	ds_read_b128 v[176:179], v251 offset:20480
	ds_read_b128 v[180:183], v251 offset:21504
	ds_read_b128 v[184:187], v251 offset:22528
	ds_read_b128 v[188:191], v251 offset:23552
	global_load_lds_dwordx4 v[220:221], off
	v_lshl_add_u64 v[222:223], s[80:81], 0, v[170:171]
	s_mov_b32 m0, s21
	s_nop 0
	global_load_lds_dwordx4 v[222:223], off
	s_barrier
	s_waitcnt lgkmcnt(0)
	s_waitcnt lgkmcnt(0)
	v_mfma_f32_16x16x32_bf16 v[92:95], v[48:51], v[116:119], 0
	v_mfma_f32_16x16x32_bf16 v[88:91], v[56:59], v[116:119], 0
	v_mfma_f32_16x16x32_bf16 v[44:47], v[48:51], v[132:135], 0
	v_mfma_f32_16x16x32_bf16 v[40:43], v[56:59], v[132:135], 0
	v_mfma_f32_16x16x32_bf16 v[28:31], v[48:51], v[176:179], 0
	v_mfma_f32_16x16x32_bf16 v[24:27], v[56:59], v[176:179], 0
	v_mfma_f32_16x16x32_bf16 v[12:15], v[48:51], v[184:187], 0
	v_mfma_f32_16x16x32_bf16 v[8:11], v[56:59], v[184:187], 0
	v_mfma_f32_16x16x32_bf16 v[92:95], v[52:55], v[128:131], v[92:95]
	v_mfma_f32_16x16x32_bf16 v[88:91], v[60:63], v[128:131], v[88:91]
	v_mfma_f32_16x16x32_bf16 v[44:47], v[52:55], v[144:147], v[44:47]
	v_mfma_f32_16x16x32_bf16 v[40:43], v[60:63], v[144:147], v[40:43]
	v_mfma_f32_16x16x32_bf16 v[28:31], v[52:55], v[180:183], v[28:31]
	v_mfma_f32_16x16x32_bf16 v[24:27], v[60:63], v[180:183], v[24:27]
	v_mfma_f32_16x16x32_bf16 v[12:15], v[52:55], v[188:191], v[12:15]
	v_mfma_f32_16x16x32_bf16 v[8:11], v[60:63], v[188:191], v[8:11]
	s_barrier
	s_add_u32 s66, s0, 0x80000
	s_addc_u32 s67, s1, 0
	s_add_i32 s51, s68, s19
	v_lshl_add_u64 v[48:49], s[66:67], 0, v[160:161]
	s_mov_b32 m0, s51
	s_nop 0
	global_load_lds_dwordx4 v[48:49], off
	v_lshl_add_u64 v[48:49], s[66:67], 0, v[170:171]
	s_add_i32 m0, s51, 0x2000
	s_nop 0
	global_load_lds_dwordx4 v[48:49], off
	s_waitcnt vmcnt(6)
	s_barrier
	v_mfma_f32_16x16x32_bf16 v[36:39], v[192:195], v[132:135], 0
	v_mfma_f32_16x16x32_bf16 v[32:35], v[200:203], v[132:135], 0
	v_mfma_f32_16x16x32_bf16 v[20:23], v[192:195], v[176:179], 0
	v_mfma_f32_16x16x32_bf16 v[16:19], v[200:203], v[176:179], 0
	v_mfma_f32_16x16x32_bf16 v[4:7], v[192:195], v[184:187], 0
	v_mfma_f32_16x16x32_bf16 v[0:3], v[200:203], v[184:187], 0
	v_mfma_f32_16x16x32_bf16 v[48:51], v[192:195], v[116:119], 0
	v_mfma_f32_16x16x32_bf16 v[52:55], v[200:203], v[116:119], 0
	v_mfma_f32_16x16x32_bf16 v[36:39], v[196:199], v[144:147], v[36:39]
	v_mfma_f32_16x16x32_bf16 v[32:35], v[204:207], v[144:147], v[32:35]
	v_mfma_f32_16x16x32_bf16 v[20:23], v[196:199], v[180:183], v[20:23]
	v_mfma_f32_16x16x32_bf16 v[16:19], v[204:207], v[180:183], v[16:19]
	v_mfma_f32_16x16x32_bf16 v[4:7], v[196:199], v[188:191], v[4:7]
	v_mfma_f32_16x16x32_bf16 v[0:3], v[204:207], v[188:191], v[0:3]
	v_mfma_f32_16x16x32_bf16 v[48:51], v[196:199], v[128:131], v[48:51]
	v_mfma_f32_16x16x32_bf16 v[52:55], v[204:207], v[128:131], v[52:55]
	s_add_i32 s51, 0, 0x18000
	v_add_u32_e32 v84, s51, v249
	s_barrier
	ds_read_b128 v[56:59], v84
	ds_read_b128 v[60:63], v84 offset:1024
	ds_read_b128 v[80:83], v84 offset:2048
	ds_read_b128 v[84:87], v84 offset:3072
	ds_read_b128 v[116:119], v251 offset:32768
	ds_read_b128 v[128:131], v251 offset:33792
	ds_read_b128 v[176:179], v251 offset:34816
	ds_read_b128 v[180:183], v251 offset:35840
	ds_read_b128 v[184:187], v251 offset:36864
	ds_read_b128 v[188:191], v251 offset:37888
	ds_read_b128 v[192:195], v251 offset:38912
	ds_read_b128 v[196:199], v251 offset:39936
	s_waitcnt lgkmcnt(8)
	s_barrier
	s_waitcnt lgkmcnt(0)
	s_waitcnt lgkmcnt(0)
	v_mfma_f32_16x16x32_bf16 v[132:135], v[56:59], v[116:119], v[156:159]
	v_mfma_f32_16x16x32_bf16 v[156:159], v[60:63], v[128:131], v[132:135]
	v_mfma_f32_16x16x32_bf16 v[132:135], v[80:83], v[116:119], v[152:155]
	v_mfma_f32_16x16x32_bf16 v[152:155], v[84:87], v[128:131], v[132:135]
	v_mfma_f32_16x16x32_bf16 v[132:135], v[56:59], v[176:179], v[140:143]
	v_mfma_f32_16x16x32_bf16 v[140:143], v[60:63], v[180:183], v[132:135]
	v_mfma_f32_16x16x32_bf16 v[132:135], v[80:83], v[176:179], v[136:139]
	v_mfma_f32_16x16x32_bf16 v[124:127], v[56:59], v[184:187], v[124:127]
	v_mfma_f32_16x16x32_bf16 v[120:123], v[80:83], v[184:187], v[120:123]
	v_mfma_f32_16x16x32_bf16 v[108:111], v[56:59], v[192:195], v[108:111]
	v_mfma_f32_16x16x32_bf16 v[104:107], v[80:83], v[192:195], v[104:107]
	v_mfma_f32_16x16x32_bf16 v[136:139], v[84:87], v[180:183], v[132:135]
	v_mfma_f32_16x16x32_bf16 v[124:127], v[60:63], v[188:191], v[124:127]
	v_mfma_f32_16x16x32_bf16 v[120:123], v[84:87], v[188:191], v[120:123]
	v_mfma_f32_16x16x32_bf16 v[108:111], v[60:63], v[196:199], v[108:111]
	v_mfma_f32_16x16x32_bf16 v[104:107], v[84:87], v[196:199], v[104:107]
	s_barrier
	s_add_u32 s66, s80, 0x80000
	s_addc_u32 s67, s81, 0
	v_lshl_add_u64 v[132:133], s[66:67], 0, v[160:161]
	s_mov_b32 m0, s22
	s_nop 0
	global_load_lds_dwordx4 v[132:133], off
	v_lshl_add_u64 v[132:133], s[66:67], 0, v[170:171]
	s_mov_b32 m0, s23
	s_nop 0
	global_load_lds_dwordx4 v[132:133], off
	s_add_i32 s66, 0, 0x1c000
	v_add_u32_e32 v132, s66, v249
	s_add_i32 s51, s51, s19
	ds_read_b128 v[200:203], v132
	ds_read_b128 v[204:207], v132 offset:1024
	ds_read_b128 v[208:211], v132 offset:2048
	ds_read_b128 v[212:215], v132 offset:3072
	v_lshl_add_u64 v[132:133], v[216:217], 0, s[92:93]
	s_mov_b32 m0, s51
	s_nop 0
	global_load_lds_dwordx4 v[132:133], off
	v_lshl_add_u64 v[132:133], v[218:219], 0, s[92:93]
	s_add_i32 m0, s51, 0x2000
	s_nop 0
	global_load_lds_dwordx4 v[132:133], off
	s_barrier
	s_waitcnt lgkmcnt(0)
	s_waitcnt lgkmcnt(0)
	v_mfma_f32_16x16x32_bf16 v[64:67], v[208:211], v[116:119], v[64:67]
	v_mfma_f32_16x16x32_bf16 v[132:135], v[200:203], v[116:119], v[148:151]
	v_mfma_f32_16x16x32_bf16 v[144:147], v[212:215], v[128:131], v[64:67]
	v_mfma_f32_16x16x32_bf16 v[64:67], v[200:203], v[176:179], v[68:71]
	v_mfma_f32_16x16x32_bf16 v[148:151], v[204:207], v[128:131], v[132:135]
	v_mfma_f32_16x16x32_bf16 v[132:135], v[204:207], v[180:183], v[64:67]
	v_mfma_f32_16x16x32_bf16 v[64:67], v[208:211], v[176:179], v[72:75]
	v_mfma_f32_16x16x32_bf16 v[128:131], v[212:215], v[180:183], v[64:67]
	v_mfma_f32_16x16x32_bf16 v[64:67], v[200:203], v[184:187], v[76:79]
	v_mfma_f32_16x16x32_bf16 v[116:119], v[204:207], v[188:191], v[64:67]
	v_mfma_f32_16x16x32_bf16 v[64:67], v[208:211], v[184:187], v[112:115]
	v_mfma_f32_16x16x32_bf16 v[112:115], v[212:215], v[188:191], v[64:67]
	v_mfma_f32_16x16x32_bf16 v[64:67], v[200:203], v[192:195], v[100:103]
	v_mfma_f32_16x16x32_bf16 v[100:103], v[204:207], v[196:199], v[64:67]
	v_mfma_f32_16x16x32_bf16 v[64:67], v[208:211], v[192:195], v[96:99]
	v_mfma_f32_16x16x32_bf16 v[96:99], v[212:215], v[196:199], v[64:67]
	s_mov_b32 m0, s24
	v_lshl_add_u64 v[192:193], v[220:221], 0, s[92:93]
	s_barrier
	s_nop 2
	ds_read_b128 v[64:67], v251 offset:49152
	ds_read_b128 v[68:71], v251 offset:50176
	ds_read_b128 v[72:75], v251 offset:51200
	ds_read_b128 v[76:79], v251 offset:52224
	ds_read_b128 v[176:179], v251 offset:53248
	ds_read_b128 v[180:183], v251 offset:54272
	ds_read_b128 v[184:187], v251 offset:55296
	ds_read_b128 v[188:191], v251 offset:56320
	global_load_lds_dwordx4 v[192:193], off
	v_lshl_add_u64 v[192:193], v[222:223], 0, s[92:93]
	s_mov_b32 m0, s25
	s_nop 0
	global_load_lds_dwordx4 v[192:193], off
	s_barrier
	s_waitcnt lgkmcnt(0)
	s_waitcnt lgkmcnt(0)
	v_mfma_f32_16x16x32_bf16 v[92:95], v[56:59], v[64:67], v[92:95]
	v_mfma_f32_16x16x32_bf16 v[88:91], v[80:83], v[64:67], v[88:91]
	v_mfma_f32_16x16x32_bf16 v[44:47], v[56:59], v[72:75], v[44:47]
	v_mfma_f32_16x16x32_bf16 v[40:43], v[80:83], v[72:75], v[40:43]
	v_mfma_f32_16x16x32_bf16 v[28:31], v[56:59], v[176:179], v[28:31]
	v_mfma_f32_16x16x32_bf16 v[24:27], v[80:83], v[176:179], v[24:27]
	v_mfma_f32_16x16x32_bf16 v[12:15], v[56:59], v[184:187], v[12:15]
	v_mfma_f32_16x16x32_bf16 v[8:11], v[80:83], v[184:187], v[8:11]
	v_mfma_f32_16x16x32_bf16 v[92:95], v[60:63], v[68:71], v[92:95]
	v_mfma_f32_16x16x32_bf16 v[88:91], v[84:87], v[68:71], v[88:91]
	v_mfma_f32_16x16x32_bf16 v[44:47], v[60:63], v[76:79], v[44:47]
	v_mfma_f32_16x16x32_bf16 v[40:43], v[84:87], v[76:79], v[40:43]
	v_mfma_f32_16x16x32_bf16 v[28:31], v[60:63], v[180:183], v[28:31]
	v_mfma_f32_16x16x32_bf16 v[24:27], v[84:87], v[180:183], v[24:27]
	v_mfma_f32_16x16x32_bf16 v[12:15], v[60:63], v[188:191], v[12:15]
	v_mfma_f32_16x16x32_bf16 v[8:11], v[84:87], v[188:191], v[8:11]
	s_barrier
	s_add_u32 s0, s0, 0x80080
	s_addc_u32 s1, s1, 0
	s_add_i32 s51, s66, s19
	v_lshl_add_u64 v[56:57], s[0:1], 0, v[160:161]
	s_mov_b32 m0, s51
	s_nop 0
	global_load_lds_dwordx4 v[56:57], off
	v_lshl_add_u64 v[56:57], s[0:1], 0, v[170:171]
	s_add_i32 m0, s51, 0x2000
	s_nop 0
	global_load_lds_dwordx4 v[56:57], off
	s_waitcnt vmcnt(6)
	s_barrier
	v_mfma_f32_16x16x32_bf16 v[48:51], v[200:203], v[64:67], v[48:51]
	v_mfma_f32_16x16x32_bf16 v[84:87], v[204:207], v[68:71], v[48:51]
	v_mfma_f32_16x16x32_bf16 v[48:51], v[208:211], v[64:67], v[52:55]
	v_mfma_f32_16x16x32_bf16 v[36:39], v[200:203], v[72:75], v[36:39]
	v_mfma_f32_16x16x32_bf16 v[32:35], v[208:211], v[72:75], v[32:35]
	v_mfma_f32_16x16x32_bf16 v[20:23], v[200:203], v[176:179], v[20:23]
	v_mfma_f32_16x16x32_bf16 v[16:19], v[208:211], v[176:179], v[16:19]
	v_mfma_f32_16x16x32_bf16 v[4:7], v[200:203], v[184:187], v[4:7]
	v_mfma_f32_16x16x32_bf16 v[0:3], v[208:211], v[184:187], v[0:3]
	v_mfma_f32_16x16x32_bf16 v[80:83], v[212:215], v[68:71], v[48:51]
	v_mfma_f32_16x16x32_bf16 v[36:39], v[204:207], v[76:79], v[36:39]
	v_mfma_f32_16x16x32_bf16 v[32:35], v[212:215], v[76:79], v[32:35]
	v_mfma_f32_16x16x32_bf16 v[20:23], v[204:207], v[180:183], v[20:23]
	v_mfma_f32_16x16x32_bf16 v[16:19], v[212:215], v[180:183], v[16:19]
	v_mfma_f32_16x16x32_bf16 v[4:7], v[204:207], v[188:191], v[4:7]
	v_mfma_f32_16x16x32_bf16 v[0:3], v[212:215], v[188:191], v[0:3]
	s_add_i32 s50, s50, 2
	s_add_u32 s8, s8, 0x100
	s_addc_u32 s9, s9, 0
	s_add_u32 s48, s48, 0x100
	s_addc_u32 s49, s49, 0
	s_cmp_gt_u32 s50, 29
	s_barrier

.LBB0_1055:
	s_ashr_i32 s47, s46, 31
	v_cmp_lt_i64_e32 vcc, s[14:15], v[168:169]
	s_lshl_b64 s[14:15], s[46:47], 20
	s_add_u32 s74, s28, s14
	s_addc_u32 s75, s29, s15
	s_and_b64 s[14:15], vcc, exec
	s_cselect_b32 s14, s75, s13
	s_cselect_b32 s15, s74, s12
	s_ashr_i32 s73, s72, 31
	s_lshl_b64 s[16:17], s[72:73], 20
	s_add_u32 s76, s19, s16
	s_addc_u32 s77, s20, s17
	s_and_b64 s[16:17], vcc, exec
	s_cselect_b32 s16, s77, s1
	s_cselect_b32 s17, s76, s0
	s_add_u32 s78, s12, 0x80080
	s_addc_u32 s79, s13, 0
	s_add_u32 s12, s0, 0x100
	s_addc_u32 s13, s1, 0
	s_mov_b32 s47, -2
	s_add_u32 s0, s78, 0xfff80080
	s_addc_u32 s1, s79, -1
	s_add_i32 s50, 0, 0x10000
	v_add_u32_e32 v76, s50, v205
	ds_read_b128 v[64:67], v76
	ds_read_b128 v[68:71], v76 offset:1024
	ds_read_b128 v[72:75], v76 offset:2048
	ds_read_b128 v[76:79], v76 offset:3072
	s_cmp_eq_u32 s47, 28
	s_cselect_b32 s81, s14, s1
	s_cselect_b32 s80, s15, s0
	s_cselect_b32 s1, s16, s13
	s_cselect_b32 s0, s17, s12
	ds_read_b128 v[80:83], v207
	ds_read_b128 v[84:87], v207 offset:1024
	ds_read_b128 v[88:91], v207 offset:2048
	ds_read_b128 v[92:95], v207 offset:3072
	ds_read_b128 v[180:183], v207 offset:4096
	ds_read_b128 v[184:187], v207 offset:5120
	ds_read_b128 v[188:191], v207 offset:6144
	ds_read_b128 v[192:195], v207 offset:7168
	s_waitcnt lgkmcnt(8)
	s_barrier
	s_waitcnt lgkmcnt(0)
	s_waitcnt lgkmcnt(0)
	v_mfma_f32_16x16x32_bf16 v[156:159], v[64:67], v[80:83], 0
	v_mfma_f32_16x16x32_bf16 v[152:155], v[72:75], v[80:83], 0
	v_mfma_f32_16x16x32_bf16 v[148:151], v[64:67], v[88:91], 0
	v_mfma_f32_16x16x32_bf16 v[140:143], v[72:75], v[88:91], 0
	v_mfma_f32_16x16x32_bf16 v[132:135], v[64:67], v[180:183], 0
	v_mfma_f32_16x16x32_bf16 v[124:127], v[72:75], v[180:183], 0
	v_mfma_f32_16x16x32_bf16 v[116:119], v[64:67], v[188:191], 0
	v_mfma_f32_16x16x32_bf16 v[108:111], v[72:75], v[188:191], 0
	v_mfma_f32_16x16x32_bf16 v[156:159], v[68:71], v[84:87], v[156:159]
	v_mfma_f32_16x16x32_bf16 v[152:155], v[76:79], v[84:87], v[152:155]
	v_mfma_f32_16x16x32_bf16 v[148:151], v[68:71], v[92:95], v[148:151]
	v_mfma_f32_16x16x32_bf16 v[140:143], v[76:79], v[92:95], v[140:143]
	v_mfma_f32_16x16x32_bf16 v[132:135], v[68:71], v[184:187], v[132:135]
	v_mfma_f32_16x16x32_bf16 v[124:127], v[76:79], v[184:187], v[124:127]
	v_mfma_f32_16x16x32_bf16 v[116:119], v[68:71], v[192:195], v[116:119]
	v_mfma_f32_16x16x32_bf16 v[108:111], v[76:79], v[192:195], v[108:111]
	s_barrier
	v_lshl_add_u64 v[196:197], s[78:79], 0, v[176:177]
	s_add_i32 m0, s22, 0xc000
	s_nop 0
	global_load_lds_dwordx4 v[196:197], off
	v_lshl_add_u64 v[196:197], s[78:79], 0, v[178:179]
	s_add_i32 m0, s22, 0xe000
	s_nop 0
	global_load_lds_dwordx4 v[196:197], off
	s_add_i32 s66, 0, 0x14000
	s_add_i32 s50, s50, s21
	v_add_u32_e32 v212, s66, v205
	v_lshl_add_u64 v[224:225], s[0:1], 0, v[160:161]
	s_mov_b32 m0, s50
	ds_read_b128 v[196:199], v212
	ds_read_b128 v[200:203], v212 offset:1024
	ds_read_b128 v[208:211], v212 offset:2048
	ds_read_b128 v[212:215], v212 offset:3072
	global_load_lds_dwordx4 v[224:225], off
	v_lshl_add_u64 v[226:227], s[0:1], 0, v[170:171]
	s_add_i32 m0, s50, 0x2000
	s_nop 0
	global_load_lds_dwordx4 v[226:227], off
	s_barrier
	s_waitcnt lgkmcnt(0)
	s_waitcnt lgkmcnt(0)
	v_mfma_f32_16x16x32_bf16 v[144:147], v[196:199], v[80:83], 0
	v_mfma_f32_16x16x32_bf16 v[80:83], v[208:211], v[80:83], 0
	v_mfma_f32_16x16x32_bf16 v[144:147], v[200:203], v[84:87], v[144:147]
	v_mfma_f32_16x16x32_bf16 v[80:83], v[212:215], v[84:87], v[80:83]
	v_mfma_f32_16x16x32_bf16 v[84:87], v[196:199], v[88:91], 0
	v_mfma_f32_16x16x32_bf16 v[88:91], v[208:211], v[88:91], 0
	v_mfma_f32_16x16x32_bf16 v[104:107], v[208:211], v[180:183], 0
	v_mfma_f32_16x16x32_bf16 v[100:103], v[196:199], v[188:191], 0
	v_mfma_f32_16x16x32_bf16 v[96:99], v[208:211], v[188:191], 0
	v_mfma_f32_16x16x32_bf16 v[84:87], v[200:203], v[92:95], v[84:87]
	v_mfma_f32_16x16x32_bf16 v[88:91], v[212:215], v[92:95], v[88:91]
	v_mfma_f32_16x16x32_bf16 v[92:95], v[196:199], v[180:183], 0
	v_mfma_f32_16x16x32_bf16 v[104:107], v[212:215], v[184:187], v[104:107]
	v_mfma_f32_16x16x32_bf16 v[100:103], v[200:203], v[192:195], v[100:103]
	v_mfma_f32_16x16x32_bf16 v[96:99], v[212:215], v[192:195], v[96:99]
	v_mfma_f32_16x16x32_bf16 v[92:95], v[200:203], v[184:187], v[92:95]
	s_mov_b32 m0, s22
	v_lshl_add_u64 v[228:229], s[80:81], 0, v[174:175]
	s_barrier
	ds_read_b128 v[112:115], v207 offset:16384
	ds_read_b128 v[120:123], v207 offset:17408
	ds_read_b128 v[128:131], v207 offset:18432
	ds_read_b128 v[136:139], v207 offset:19456
	ds_read_b128 v[180:183], v207 offset:20480
	ds_read_b128 v[184:187], v207 offset:21504
	ds_read_b128 v[188:191], v207 offset:22528
	ds_read_b128 v[192:195], v207 offset:23552
	global_load_lds_dwordx4 v[228:229], off
	v_lshl_add_u64 v[230:231], s[80:81], 0, v[172:173]
	s_mov_b32 m0, s23
	s_nop 0
	global_load_lds_dwordx4 v[230:231], off
	s_waitcnt vmcnt(10)
	s_barrier
	s_waitcnt lgkmcnt(0)
	s_waitcnt lgkmcnt(0)
	v_mfma_f32_16x16x32_bf16 v[60:63], v[64:67], v[112:115], 0
	v_mfma_f32_16x16x32_bf16 v[56:59], v[72:75], v[112:115], 0
	v_mfma_f32_16x16x32_bf16 v[44:47], v[64:67], v[128:131], 0
	v_mfma_f32_16x16x32_bf16 v[40:43], v[72:75], v[128:131], 0
	v_mfma_f32_16x16x32_bf16 v[28:31], v[64:67], v[180:183], 0
	v_mfma_f32_16x16x32_bf16 v[24:27], v[72:75], v[180:183], 0
	v_mfma_f32_16x16x32_bf16 v[12:15], v[64:67], v[188:191], 0
	v_mfma_f32_16x16x32_bf16 v[8:11], v[72:75], v[188:191], 0
	v_mfma_f32_16x16x32_bf16 v[60:63], v[68:71], v[120:123], v[60:63]
	v_mfma_f32_16x16x32_bf16 v[56:59], v[76:79], v[120:123], v[56:59]
	v_mfma_f32_16x16x32_bf16 v[44:47], v[68:71], v[136:139], v[44:47]
	v_mfma_f32_16x16x32_bf16 v[40:43], v[76:79], v[136:139], v[40:43]
	v_mfma_f32_16x16x32_bf16 v[28:31], v[68:71], v[184:187], v[28:31]
	v_mfma_f32_16x16x32_bf16 v[24:27], v[76:79], v[184:187], v[24:27]
	v_mfma_f32_16x16x32_bf16 v[12:15], v[68:71], v[192:195], v[12:15]
	v_mfma_f32_16x16x32_bf16 v[8:11], v[76:79], v[192:195], v[8:11]
	s_barrier
	s_add_u32 s50, s0, 0x80000
	s_addc_u32 s51, s1, 0
	s_add_i32 s66, s66, s21
	v_lshl_add_u64 v[64:65], s[50:51], 0, v[160:161]
	s_mov_b32 m0, s66
	s_nop 0
	global_load_lds_dwordx4 v[64:65], off
	v_lshl_add_u64 v[64:65], s[50:51], 0, v[170:171]
	s_add_i32 m0, s66, 0x2000
	s_nop 0
	global_load_lds_dwordx4 v[64:65], off
	v_add_u32_e32 v76, 0x18000, v205
	ds_read_b128 v[64:67], v76
	ds_read_b128 v[68:71], v76 offset:1024
	ds_read_b128 v[72:75], v76 offset:2048
	ds_read_b128 v[76:79], v76 offset:3072
	s_waitcnt vmcnt(6)
	s_barrier
	v_mfma_f32_16x16x32_bf16 v[52:55], v[196:199], v[112:115], 0
	v_mfma_f32_16x16x32_bf16 v[48:51], v[208:211], v[112:115], 0
	v_mfma_f32_16x16x32_bf16 v[36:39], v[196:199], v[128:131], 0
	v_mfma_f32_16x16x32_bf16 v[32:35], v[208:211], v[128:131], 0
	v_mfma_f32_16x16x32_bf16 v[20:23], v[196:199], v[180:183], 0
	v_mfma_f32_16x16x32_bf16 v[16:19], v[208:211], v[180:183], 0
	v_mfma_f32_16x16x32_bf16 v[4:7], v[196:199], v[188:191], 0
	v_mfma_f32_16x16x32_bf16 v[0:3], v[208:211], v[188:191], 0
	v_mfma_f32_16x16x32_bf16 v[52:55], v[200:203], v[120:123], v[52:55]
	v_mfma_f32_16x16x32_bf16 v[48:51], v[212:215], v[120:123], v[48:51]
	v_mfma_f32_16x16x32_bf16 v[36:39], v[200:203], v[136:139], v[36:39]
	v_mfma_f32_16x16x32_bf16 v[32:35], v[212:215], v[136:139], v[32:35]
	v_mfma_f32_16x16x32_bf16 v[20:23], v[200:203], v[184:187], v[20:23]
	v_mfma_f32_16x16x32_bf16 v[16:19], v[212:215], v[184:187], v[16:19]
	v_mfma_f32_16x16x32_bf16 v[4:7], v[200:203], v[192:195], v[4:7]
	v_mfma_f32_16x16x32_bf16 v[0:3], v[212:215], v[192:195], v[0:3]
	s_add_i32 s66, 0, 0x18000
	s_barrier
	ds_read_b128 v[112:115], v207 offset:32768
	ds_read_b128 v[120:123], v207 offset:33792
	ds_read_b128 v[180:183], v207 offset:34816
	ds_read_b128 v[184:187], v207 offset:35840
	ds_read_b128 v[188:191], v207 offset:36864
	ds_read_b128 v[192:195], v207 offset:37888
	ds_read_b128 v[196:199], v207 offset:38912
	ds_read_b128 v[200:203], v207 offset:39936
	s_waitcnt lgkmcnt(8)
	s_barrier
	s_waitcnt lgkmcnt(0)
	s_waitcnt lgkmcnt(0)
	v_mfma_f32_16x16x32_bf16 v[128:131], v[64:67], v[112:115], v[156:159]
	v_mfma_f32_16x16x32_bf16 v[156:159], v[68:71], v[120:123], v[128:131]
	v_mfma_f32_16x16x32_bf16 v[128:131], v[72:75], v[112:115], v[152:155]
	v_mfma_f32_16x16x32_bf16 v[152:155], v[76:79], v[120:123], v[128:131]
	v_mfma_f32_16x16x32_bf16 v[128:131], v[64:67], v[180:183], v[148:151]
	v_mfma_f32_16x16x32_bf16 v[148:151], v[68:71], v[184:187], v[128:131]
	v_mfma_f32_16x16x32_bf16 v[128:131], v[72:75], v[180:183], v[140:143]
	v_mfma_f32_16x16x32_bf16 v[140:143], v[76:79], v[184:187], v[128:131]
	v_mfma_f32_16x16x32_bf16 v[128:131], v[64:67], v[188:191], v[132:135]
	v_mfma_f32_16x16x32_bf16 v[124:127], v[72:75], v[188:191], v[124:127]
	v_mfma_f32_16x16x32_bf16 v[116:119], v[64:67], v[196:199], v[116:119]
	v_mfma_f32_16x16x32_bf16 v[108:111], v[72:75], v[196:199], v[108:111]
	v_mfma_f32_16x16x32_bf16 v[132:135], v[68:71], v[192:195], v[128:131]
	v_mfma_f32_16x16x32_bf16 v[124:127], v[76:79], v[192:195], v[124:127]
	v_mfma_f32_16x16x32_bf16 v[116:119], v[68:71], v[200:203], v[116:119]
	v_mfma_f32_16x16x32_bf16 v[108:111], v[76:79], v[200:203], v[108:111]
	s_barrier
	s_add_u32 s50, s80, 0x80000
	s_addc_u32 s51, s81, 0
	v_lshl_add_u64 v[128:129], s[50:51], 0, v[174:175]
	s_mov_b32 m0, s24
	s_nop 0
	global_load_lds_dwordx4 v[128:129], off
	v_lshl_add_u64 v[128:129], s[50:51], 0, v[172:173]
	s_mov_b32 m0, s25
	s_nop 0
	global_load_lds_dwordx4 v[128:129], off
	s_add_i32 s50, 0, 0x1c000
	v_add_u32_e32 v128, s50, v205
	s_add_i32 s51, s66, s21
	ds_read_b128 v[208:211], v128
	ds_read_b128 v[212:215], v128 offset:1024
	ds_read_b128 v[216:219], v128 offset:2048
	ds_read_b128 v[220:223], v128 offset:3072
	v_lshl_add_u64 v[128:129], v[224:225], 0, s[92:93]
	s_mov_b32 m0, s51
	s_nop 0
	global_load_lds_dwordx4 v[128:129], off
	v_lshl_add_u64 v[128:129], v[226:227], 0, s[92:93]
	s_add_i32 m0, s51, 0x2000
	s_nop 0
	global_load_lds_dwordx4 v[128:129], off
	s_barrier
	s_waitcnt lgkmcnt(0)
	s_waitcnt lgkmcnt(0)
	v_mfma_f32_16x16x32_bf16 v[80:83], v[216:219], v[112:115], v[80:83]
	v_mfma_f32_16x16x32_bf16 v[128:131], v[208:211], v[112:115], v[144:147]
	v_mfma_f32_16x16x32_bf16 v[136:139], v[220:223], v[120:123], v[80:83]
	v_mfma_f32_16x16x32_bf16 v[80:83], v[208:211], v[180:183], v[84:87]
	v_mfma_f32_16x16x32_bf16 v[144:147], v[212:215], v[120:123], v[128:131]
	v_mfma_f32_16x16x32_bf16 v[128:131], v[212:215], v[184:187], v[80:83]
	v_mfma_f32_16x16x32_bf16 v[80:83], v[216:219], v[180:183], v[88:91]
	v_mfma_f32_16x16x32_bf16 v[120:123], v[220:223], v[184:187], v[80:83]
	v_mfma_f32_16x16x32_bf16 v[80:83], v[208:211], v[188:191], v[92:95]
	v_mfma_f32_16x16x32_bf16 v[112:115], v[212:215], v[192:195], v[80:83]
	v_mfma_f32_16x16x32_bf16 v[80:83], v[216:219], v[188:191], v[104:107]
	v_mfma_f32_16x16x32_bf16 v[104:107], v[220:223], v[192:195], v[80:83]
	v_mfma_f32_16x16x32_bf16 v[80:83], v[208:211], v[196:199], v[100:103]
	v_mfma_f32_16x16x32_bf16 v[100:103], v[212:215], v[200:203], v[80:83]
	v_mfma_f32_16x16x32_bf16 v[80:83], v[216:219], v[196:199], v[96:99]
	v_mfma_f32_16x16x32_bf16 v[96:99], v[220:223], v[200:203], v[80:83]
	s_mov_b32 m0, s26
	v_lshl_add_u64 v[196:197], v[228:229], 0, s[92:93]
	s_barrier
	s_nop 2
	ds_read_b128 v[80:83], v207 offset:49152
	ds_read_b128 v[84:87], v207 offset:50176
	ds_read_b128 v[88:91], v207 offset:51200
	ds_read_b128 v[92:95], v207 offset:52224
	ds_read_b128 v[180:183], v207 offset:53248
	ds_read_b128 v[184:187], v207 offset:54272
	ds_read_b128 v[188:191], v207 offset:55296
	ds_read_b128 v[192:195], v207 offset:56320
	global_load_lds_dwordx4 v[196:197], off
	v_lshl_add_u64 v[196:197], v[230:231], 0, s[92:93]
	s_mov_b32 m0, s27
	s_nop 0
	global_load_lds_dwordx4 v[196:197], off
	s_barrier
	s_waitcnt lgkmcnt(0)
	s_waitcnt lgkmcnt(0)
	v_mfma_f32_16x16x32_bf16 v[60:63], v[64:67], v[80:83], v[60:63]
	v_mfma_f32_16x16x32_bf16 v[56:59], v[72:75], v[80:83], v[56:59]
	v_mfma_f32_16x16x32_bf16 v[44:47], v[64:67], v[88:91], v[44:47]
	v_mfma_f32_16x16x32_bf16 v[40:43], v[72:75], v[88:91], v[40:43]
	v_mfma_f32_16x16x32_bf16 v[28:31], v[64:67], v[180:183], v[28:31]
	v_mfma_f32_16x16x32_bf16 v[24:27], v[72:75], v[180:183], v[24:27]
	v_mfma_f32_16x16x32_bf16 v[12:15], v[64:67], v[188:191], v[12:15]
	v_mfma_f32_16x16x32_bf16 v[8:11], v[72:75], v[188:191], v[8:11]
	v_mfma_f32_16x16x32_bf16 v[60:63], v[68:71], v[84:87], v[60:63]
	v_mfma_f32_16x16x32_bf16 v[56:59], v[76:79], v[84:87], v[56:59]
	v_mfma_f32_16x16x32_bf16 v[44:47], v[68:71], v[92:95], v[44:47]
	v_mfma_f32_16x16x32_bf16 v[40:43], v[76:79], v[92:95], v[40:43]
	v_mfma_f32_16x16x32_bf16 v[28:31], v[68:71], v[184:187], v[28:31]
	v_mfma_f32_16x16x32_bf16 v[24:27], v[76:79], v[184:187], v[24:27]
	v_mfma_f32_16x16x32_bf16 v[12:15], v[68:71], v[192:195], v[12:15]
	v_mfma_f32_16x16x32_bf16 v[8:11], v[76:79], v[192:195], v[8:11]
	s_barrier
	s_add_u32 s0, s0, 0x80080
	s_addc_u32 s1, s1, 0
	s_add_i32 s50, s50, s21
	v_lshl_add_u64 v[64:65], s[0:1], 0, v[160:161]
	s_mov_b32 m0, s50
	s_nop 0
	global_load_lds_dwordx4 v[64:65], off
	v_lshl_add_u64 v[64:65], s[0:1], 0, v[170:171]
	s_add_i32 m0, s50, 0x2000
	s_nop 0
	global_load_lds_dwordx4 v[64:65], off
	s_waitcnt vmcnt(6)
	s_barrier
	v_mfma_f32_16x16x32_bf16 v[52:55], v[208:211], v[80:83], v[52:55]
	v_mfma_f32_16x16x32_bf16 v[48:51], v[216:219], v[80:83], v[48:51]
	v_mfma_f32_16x16x32_bf16 v[36:39], v[208:211], v[88:91], v[36:39]
	v_mfma_f32_16x16x32_bf16 v[32:35], v[216:219], v[88:91], v[32:35]
	v_mfma_f32_16x16x32_bf16 v[20:23], v[208:211], v[180:183], v[20:23]
	v_mfma_f32_16x16x32_bf16 v[16:19], v[216:219], v[180:183], v[16:19]
	v_mfma_f32_16x16x32_bf16 v[4:7], v[208:211], v[188:191], v[4:7]
	v_mfma_f32_16x16x32_bf16 v[0:3], v[216:219], v[188:191], v[0:3]
	v_mfma_f32_16x16x32_bf16 v[52:55], v[212:215], v[84:87], v[52:55]
	v_mfma_f32_16x16x32_bf16 v[48:51], v[220:223], v[84:87], v[48:51]
	v_mfma_f32_16x16x32_bf16 v[36:39], v[212:215], v[92:95], v[36:39]
	v_mfma_f32_16x16x32_bf16 v[32:35], v[220:223], v[92:95], v[32:35]
	v_mfma_f32_16x16x32_bf16 v[20:23], v[212:215], v[184:187], v[20:23]
	v_mfma_f32_16x16x32_bf16 v[16:19], v[220:223], v[184:187], v[16:19]
	v_mfma_f32_16x16x32_bf16 v[4:7], v[212:215], v[192:195], v[4:7]
	v_mfma_f32_16x16x32_bf16 v[0:3], v[220:223], v[192:195], v[0:3]
	s_add_i32 s47, s47, 2
	s_add_u32 s78, s78, 0x100
	s_addc_u32 s79, s79, 0
	s_add_u32 s12, s12, 0x100
	s_addc_u32 s13, s13, 0
	s_cmp_gt_u32 s47, 29
	s_barrier

.LBB0_1226:
	s_ashr_i32 s45, s44, 31
	v_cmp_lt_i64_e32 vcc, s[12:13], v[164:165]
	s_lshl_b64 s[12:13], s[44:45], 22
	s_add_u32 s48, s36, s12
	s_addc_u32 s49, s37, s13
	s_and_b64 s[12:13], vcc, exec
	s_cselect_b32 s12, s49, s5
	s_cselect_b32 s13, s48, s4
	s_ashr_i32 s47, s46, 31
	s_lshl_b64 s[14:15], s[46:47], 22
	s_add_u32 s50, s19, s14
	s_addc_u32 s51, s20, s15
	s_and_b64 s[14:15], vcc, exec
	s_cselect_b32 s14, s51, s73
	s_cselect_b32 s15, s50, s72
	s_add_u32 s4, s4, 0x200080
	s_addc_u32 s5, s5, 0
	s_add_u32 s45, s72, 0x100
	s_addc_u32 s47, s73, 0
	s_mov_b32 s66, -2
	s_add_u32 s67, s4, 0xffe00080
	s_addc_u32 s68, s5, -1
	s_add_i32 s71, 0, 0x10000
	v_add_u32_e32 v60, s71, v249
	ds_read_b128 v[48:51], v60
	ds_read_b128 v[52:55], v60 offset:1024
	ds_read_b128 v[56:59], v60 offset:2048
	ds_read_b128 v[60:63], v60 offset:3072
	s_cmpk_eq_i32 s66, 0x7c
	s_cselect_b32 s75, s12, s68
	s_cselect_b32 s74, s13, s67
	s_cselect_b32 s73, s14, s47
	s_cselect_b32 s72, s15, s45
	ds_read_b128 v[64:67], v251
	ds_read_b128 v[68:71], v251 offset:1024
	ds_read_b128 v[72:75], v251 offset:2048
	ds_read_b128 v[76:79], v251 offset:3072
	ds_read_b128 v[176:179], v251 offset:4096
	ds_read_b128 v[180:183], v251 offset:5120
	ds_read_b128 v[184:187], v251 offset:6144
	ds_read_b128 v[188:191], v251 offset:7168
	s_waitcnt lgkmcnt(8)
	s_barrier
	s_waitcnt lgkmcnt(0)
	s_waitcnt lgkmcnt(0)
	v_mfma_f32_16x16x32_bf16 v[156:159], v[48:51], v[64:67], 0
	v_mfma_f32_16x16x32_bf16 v[152:155], v[56:59], v[64:67], 0
	v_mfma_f32_16x16x32_bf16 v[140:143], v[48:51], v[72:75], 0
	v_mfma_f32_16x16x32_bf16 v[136:139], v[56:59], v[72:75], 0
	v_mfma_f32_16x16x32_bf16 v[124:127], v[48:51], v[176:179], 0
	v_mfma_f32_16x16x32_bf16 v[120:123], v[56:59], v[176:179], 0
	v_mfma_f32_16x16x32_bf16 v[108:111], v[48:51], v[184:187], 0
	v_mfma_f32_16x16x32_bf16 v[104:107], v[56:59], v[184:187], 0
	v_mfma_f32_16x16x32_bf16 v[156:159], v[52:55], v[68:71], v[156:159]
	v_mfma_f32_16x16x32_bf16 v[152:155], v[60:63], v[68:71], v[152:155]
	v_mfma_f32_16x16x32_bf16 v[140:143], v[52:55], v[76:79], v[140:143]
	v_mfma_f32_16x16x32_bf16 v[136:139], v[60:63], v[76:79], v[136:139]
	v_mfma_f32_16x16x32_bf16 v[124:127], v[52:55], v[180:183], v[124:127]
	v_mfma_f32_16x16x32_bf16 v[120:123], v[60:63], v[180:183], v[120:123]
	v_mfma_f32_16x16x32_bf16 v[108:111], v[52:55], v[188:191], v[108:111]
	v_mfma_f32_16x16x32_bf16 v[104:107], v[60:63], v[188:191], v[104:107]
	s_barrier
	v_lshl_add_u64 v[192:193], s[4:5], 0, v[172:173]
	s_add_i32 m0, s22, 0xc000
	s_nop 0
	global_load_lds_dwordx4 v[192:193], off
	v_lshl_add_u64 v[192:193], s[4:5], 0, v[174:175]
	s_add_i32 m0, s22, 0xe000
	s_nop 0
	global_load_lds_dwordx4 v[192:193], off
	s_add_i32 s67, 0, 0x14000
	s_add_i32 s68, s71, s21
	v_add_u32_e32 v204, s67, v249
	v_lshl_add_u64 v[216:217], s[72:73], 0, v[160:161]
	s_mov_b32 m0, s68
	ds_read_b128 v[192:195], v204
	ds_read_b128 v[196:199], v204 offset:1024
	ds_read_b128 v[200:203], v204 offset:2048
	ds_read_b128 v[204:207], v204 offset:3072
	global_load_lds_dwordx4 v[216:217], off
	v_lshl_add_u64 v[218:219], s[72:73], 0, v[170:171]
	s_add_i32 m0, s68, 0x2000
	s_nop 0
	global_load_lds_dwordx4 v[218:219], off
	s_barrier
	s_waitcnt lgkmcnt(0)
	s_waitcnt lgkmcnt(0)
	v_mfma_f32_16x16x32_bf16 v[148:151], v[192:195], v[64:67], 0
	v_mfma_f32_16x16x32_bf16 v[64:67], v[200:203], v[64:67], 0
	v_mfma_f32_16x16x32_bf16 v[148:151], v[196:199], v[68:71], v[148:151]
	v_mfma_f32_16x16x32_bf16 v[64:67], v[204:207], v[68:71], v[64:67]
	v_mfma_f32_16x16x32_bf16 v[68:71], v[192:195], v[72:75], 0
	v_mfma_f32_16x16x32_bf16 v[72:75], v[200:203], v[72:75], 0
	v_mfma_f32_16x16x32_bf16 v[112:115], v[200:203], v[176:179], 0
	v_mfma_f32_16x16x32_bf16 v[100:103], v[192:195], v[184:187], 0
	v_mfma_f32_16x16x32_bf16 v[96:99], v[200:203], v[184:187], 0
	v_mfma_f32_16x16x32_bf16 v[68:71], v[196:199], v[76:79], v[68:71]
	v_mfma_f32_16x16x32_bf16 v[72:75], v[204:207], v[76:79], v[72:75]
	v_mfma_f32_16x16x32_bf16 v[76:79], v[192:195], v[176:179], 0
	v_mfma_f32_16x16x32_bf16 v[112:115], v[204:207], v[180:183], v[112:115]
	v_mfma_f32_16x16x32_bf16 v[100:103], v[196:199], v[188:191], v[100:103]
	v_mfma_f32_16x16x32_bf16 v[96:99], v[204:207], v[188:191], v[96:99]
	v_mfma_f32_16x16x32_bf16 v[76:79], v[196:199], v[180:183], v[76:79]
	s_mov_b32 m0, s22
	v_lshl_add_u64 v[220:221], s[74:75], 0, v[160:161]
	s_barrier
	ds_read_b128 v[116:119], v251 offset:16384
	ds_read_b128 v[128:131], v251 offset:17408
	ds_read_b128 v[132:135], v251 offset:18432
	ds_read_b128 v[144:147], v251 offset:19456
	ds_read_b128 v[176:179], v251 offset:20480
	ds_read_b128 v[180:183], v251 offset:21504
	ds_read_b128 v[184:187], v251 offset:22528
	ds_read_b128 v[188:191], v251 offset:23552
	global_load_lds_dwordx4 v[220:221], off
	v_lshl_add_u64 v[222:223], s[74:75], 0, v[170:171]
	s_mov_b32 m0, s23
	s_nop 0
	global_load_lds_dwordx4 v[222:223], off
	s_barrier
	s_waitcnt lgkmcnt(0)
	s_waitcnt lgkmcnt(0)
	v_mfma_f32_16x16x32_bf16 v[92:95], v[48:51], v[116:119], 0
	v_mfma_f32_16x16x32_bf16 v[88:91], v[56:59], v[116:119], 0
	v_mfma_f32_16x16x32_bf16 v[44:47], v[48:51], v[132:135], 0
	v_mfma_f32_16x16x32_bf16 v[40:43], v[56:59], v[132:135], 0
	v_mfma_f32_16x16x32_bf16 v[28:31], v[48:51], v[176:179], 0
	v_mfma_f32_16x16x32_bf16 v[24:27], v[56:59], v[176:179], 0
	v_mfma_f32_16x16x32_bf16 v[12:15], v[48:51], v[184:187], 0
	v_mfma_f32_16x16x32_bf16 v[8:11], v[56:59], v[184:187], 0
	v_mfma_f32_16x16x32_bf16 v[92:95], v[52:55], v[128:131], v[92:95]
	v_mfma_f32_16x16x32_bf16 v[88:91], v[60:63], v[128:131], v[88:91]
	v_mfma_f32_16x16x32_bf16 v[44:47], v[52:55], v[144:147], v[44:47]
	v_mfma_f32_16x16x32_bf16 v[40:43], v[60:63], v[144:147], v[40:43]
	v_mfma_f32_16x16x32_bf16 v[28:31], v[52:55], v[180:183], v[28:31]
	v_mfma_f32_16x16x32_bf16 v[24:27], v[60:63], v[180:183], v[24:27]
	v_mfma_f32_16x16x32_bf16 v[12:15], v[52:55], v[188:191], v[12:15]
	v_mfma_f32_16x16x32_bf16 v[8:11], v[60:63], v[188:191], v[8:11]
	s_barrier
	s_add_u32 s76, s72, 0x200000
	s_addc_u32 s77, s73, 0
	s_add_i32 s67, s67, s21
	v_lshl_add_u64 v[48:49], s[76:77], 0, v[160:161]
	s_mov_b32 m0, s67
	s_nop 0
	global_load_lds_dwordx4 v[48:49], off
	v_lshl_add_u64 v[48:49], s[76:77], 0, v[170:171]
	s_add_i32 m0, s67, 0x2000
	s_nop 0
	global_load_lds_dwordx4 v[48:49], off
	s_waitcnt vmcnt(6)
	s_barrier
	v_mfma_f32_16x16x32_bf16 v[36:39], v[192:195], v[132:135], 0
	v_mfma_f32_16x16x32_bf16 v[32:35], v[200:203], v[132:135], 0
	v_mfma_f32_16x16x32_bf16 v[20:23], v[192:195], v[176:179], 0
	v_mfma_f32_16x16x32_bf16 v[16:19], v[200:203], v[176:179], 0
	v_mfma_f32_16x16x32_bf16 v[4:7], v[192:195], v[184:187], 0
	v_mfma_f32_16x16x32_bf16 v[0:3], v[200:203], v[184:187], 0
	v_mfma_f32_16x16x32_bf16 v[48:51], v[192:195], v[116:119], 0
	v_mfma_f32_16x16x32_bf16 v[52:55], v[200:203], v[116:119], 0
	v_mfma_f32_16x16x32_bf16 v[36:39], v[196:199], v[144:147], v[36:39]
	v_mfma_f32_16x16x32_bf16 v[32:35], v[204:207], v[144:147], v[32:35]
	v_mfma_f32_16x16x32_bf16 v[20:23], v[196:199], v[180:183], v[20:23]
	v_mfma_f32_16x16x32_bf16 v[16:19], v[204:207], v[180:183], v[16:19]
	v_mfma_f32_16x16x32_bf16 v[4:7], v[196:199], v[188:191], v[4:7]
	v_mfma_f32_16x16x32_bf16 v[0:3], v[204:207], v[188:191], v[0:3]
	v_mfma_f32_16x16x32_bf16 v[48:51], v[196:199], v[128:131], v[48:51]
	v_mfma_f32_16x16x32_bf16 v[52:55], v[204:207], v[128:131], v[52:55]
	s_add_i32 s67, 0, 0x18000
	v_add_u32_e32 v84, s67, v249
	s_barrier
	ds_read_b128 v[56:59], v84
	ds_read_b128 v[60:63], v84 offset:1024
	ds_read_b128 v[80:83], v84 offset:2048
	ds_read_b128 v[84:87], v84 offset:3072
	ds_read_b128 v[116:119], v251 offset:32768
	ds_read_b128 v[128:131], v251 offset:33792
	ds_read_b128 v[176:179], v251 offset:34816
	ds_read_b128 v[180:183], v251 offset:35840
	ds_read_b128 v[184:187], v251 offset:36864
	ds_read_b128 v[188:191], v251 offset:37888
	ds_read_b128 v[192:195], v251 offset:38912
	ds_read_b128 v[196:199], v251 offset:39936
	s_waitcnt lgkmcnt(8)
	s_barrier
	s_waitcnt lgkmcnt(0)
	s_waitcnt lgkmcnt(0)
	v_mfma_f32_16x16x32_bf16 v[132:135], v[56:59], v[116:119], v[156:159]
	v_mfma_f32_16x16x32_bf16 v[156:159], v[60:63], v[128:131], v[132:135]
	v_mfma_f32_16x16x32_bf16 v[132:135], v[80:83], v[116:119], v[152:155]
	v_mfma_f32_16x16x32_bf16 v[152:155], v[84:87], v[128:131], v[132:135]
	v_mfma_f32_16x16x32_bf16 v[132:135], v[56:59], v[176:179], v[140:143]
	v_mfma_f32_16x16x32_bf16 v[140:143], v[60:63], v[180:183], v[132:135]
	v_mfma_f32_16x16x32_bf16 v[132:135], v[80:83], v[176:179], v[136:139]
	v_mfma_f32_16x16x32_bf16 v[124:127], v[56:59], v[184:187], v[124:127]
	v_mfma_f32_16x16x32_bf16 v[120:123], v[80:83], v[184:187], v[120:123]
	v_mfma_f32_16x16x32_bf16 v[108:111], v[56:59], v[192:195], v[108:111]
	v_mfma_f32_16x16x32_bf16 v[104:107], v[80:83], v[192:195], v[104:107]
	v_mfma_f32_16x16x32_bf16 v[136:139], v[84:87], v[180:183], v[132:135]
	v_mfma_f32_16x16x32_bf16 v[124:127], v[60:63], v[188:191], v[124:127]
	v_mfma_f32_16x16x32_bf16 v[120:123], v[84:87], v[188:191], v[120:123]
	v_mfma_f32_16x16x32_bf16 v[108:111], v[60:63], v[196:199], v[108:111]
	v_mfma_f32_16x16x32_bf16 v[104:107], v[84:87], v[196:199], v[104:107]
	s_barrier
	s_add_u32 s74, s74, 0x200000
	s_addc_u32 s75, s75, 0
	v_lshl_add_u64 v[132:133], s[74:75], 0, v[160:161]
	s_mov_b32 m0, s24
	s_nop 0
	global_load_lds_dwordx4 v[132:133], off
	v_lshl_add_u64 v[132:133], s[74:75], 0, v[170:171]
	s_mov_b32 m0, s25
	s_nop 0
	global_load_lds_dwordx4 v[132:133], off
	s_add_i32 s68, 0, 0x1c000
	v_add_u32_e32 v132, s68, v249
	s_add_i32 s67, s67, s21
	ds_read_b128 v[200:203], v132
	ds_read_b128 v[204:207], v132 offset:1024
	ds_read_b128 v[208:211], v132 offset:2048
	ds_read_b128 v[212:215], v132 offset:3072
	v_lshl_add_u64 v[132:133], v[216:217], 0, s[92:93]
	s_mov_b32 m0, s67
	s_nop 0
	global_load_lds_dwordx4 v[132:133], off
	v_lshl_add_u64 v[132:133], v[218:219], 0, s[92:93]
	s_add_i32 m0, s67, 0x2000
	s_nop 0
	global_load_lds_dwordx4 v[132:133], off
	s_barrier
	s_waitcnt lgkmcnt(0)
	s_waitcnt lgkmcnt(0)
	v_mfma_f32_16x16x32_bf16 v[64:67], v[208:211], v[116:119], v[64:67]
	v_mfma_f32_16x16x32_bf16 v[132:135], v[200:203], v[116:119], v[148:151]
	v_mfma_f32_16x16x32_bf16 v[144:147], v[212:215], v[128:131], v[64:67]
	v_mfma_f32_16x16x32_bf16 v[64:67], v[200:203], v[176:179], v[68:71]
	v_mfma_f32_16x16x32_bf16 v[148:151], v[204:207], v[128:131], v[132:135]
	v_mfma_f32_16x16x32_bf16 v[132:135], v[204:207], v[180:183], v[64:67]
	v_mfma_f32_16x16x32_bf16 v[64:67], v[208:211], v[176:179], v[72:75]
	v_mfma_f32_16x16x32_bf16 v[128:131], v[212:215], v[180:183], v[64:67]
	v_mfma_f32_16x16x32_bf16 v[64:67], v[200:203], v[184:187], v[76:79]
	v_mfma_f32_16x16x32_bf16 v[116:119], v[204:207], v[188:191], v[64:67]
	v_mfma_f32_16x16x32_bf16 v[64:67], v[208:211], v[184:187], v[112:115]
	v_mfma_f32_16x16x32_bf16 v[112:115], v[212:215], v[188:191], v[64:67]
	v_mfma_f32_16x16x32_bf16 v[64:67], v[200:203], v[192:195], v[100:103]
	v_mfma_f32_16x16x32_bf16 v[100:103], v[204:207], v[196:199], v[64:67]
	v_mfma_f32_16x16x32_bf16 v[64:67], v[208:211], v[192:195], v[96:99]
	v_mfma_f32_16x16x32_bf16 v[96:99], v[212:215], v[196:199], v[64:67]
	s_mov_b32 m0, s26
	v_lshl_add_u64 v[192:193], v[220:221], 0, s[92:93]
	s_barrier
	s_nop 2
	ds_read_b128 v[64:67], v251 offset:49152
	ds_read_b128 v[68:71], v251 offset:50176
	ds_read_b128 v[72:75], v251 offset:51200
	ds_read_b128 v[76:79], v251 offset:52224
	ds_read_b128 v[176:179], v251 offset:53248
	ds_read_b128 v[180:183], v251 offset:54272
	ds_read_b128 v[184:187], v251 offset:55296
	ds_read_b128 v[188:191], v251 offset:56320
	global_load_lds_dwordx4 v[192:193], off
	v_lshl_add_u64 v[192:193], v[222:223], 0, s[92:93]
	s_mov_b32 m0, s27
	s_nop 0
	global_load_lds_dwordx4 v[192:193], off
	s_barrier
	s_waitcnt lgkmcnt(0)
	s_waitcnt lgkmcnt(0)
	v_mfma_f32_16x16x32_bf16 v[92:95], v[56:59], v[64:67], v[92:95]
	v_mfma_f32_16x16x32_bf16 v[88:91], v[80:83], v[64:67], v[88:91]
	v_mfma_f32_16x16x32_bf16 v[44:47], v[56:59], v[72:75], v[44:47]
	v_mfma_f32_16x16x32_bf16 v[40:43], v[80:83], v[72:75], v[40:43]
	v_mfma_f32_16x16x32_bf16 v[28:31], v[56:59], v[176:179], v[28:31]
	v_mfma_f32_16x16x32_bf16 v[24:27], v[80:83], v[176:179], v[24:27]
	v_mfma_f32_16x16x32_bf16 v[12:15], v[56:59], v[184:187], v[12:15]
	v_mfma_f32_16x16x32_bf16 v[8:11], v[80:83], v[184:187], v[8:11]
	v_mfma_f32_16x16x32_bf16 v[92:95], v[60:63], v[68:71], v[92:95]
	v_mfma_f32_16x16x32_bf16 v[88:91], v[84:87], v[68:71], v[88:91]
	v_mfma_f32_16x16x32_bf16 v[44:47], v[60:63], v[76:79], v[44:47]
	v_mfma_f32_16x16x32_bf16 v[40:43], v[84:87], v[76:79], v[40:43]
	v_mfma_f32_16x16x32_bf16 v[28:31], v[60:63], v[180:183], v[28:31]
	v_mfma_f32_16x16x32_bf16 v[24:27], v[84:87], v[180:183], v[24:27]
	v_mfma_f32_16x16x32_bf16 v[12:15], v[60:63], v[188:191], v[12:15]
	v_mfma_f32_16x16x32_bf16 v[8:11], v[84:87], v[188:191], v[8:11]
	s_barrier
	s_add_u32 s72, s72, 0x200080
	s_addc_u32 s73, s73, 0
	s_add_i32 s67, s68, s21
	v_lshl_add_u64 v[56:57], s[72:73], 0, v[160:161]
	s_mov_b32 m0, s67
	s_nop 0
	global_load_lds_dwordx4 v[56:57], off
	v_lshl_add_u64 v[56:57], s[72:73], 0, v[170:171]
	s_add_i32 m0, s67, 0x2000
	s_nop 0
	global_load_lds_dwordx4 v[56:57], off
	s_waitcnt vmcnt(6)
	s_barrier
	v_mfma_f32_16x16x32_bf16 v[48:51], v[200:203], v[64:67], v[48:51]
	v_mfma_f32_16x16x32_bf16 v[84:87], v[204:207], v[68:71], v[48:51]
	v_mfma_f32_16x16x32_bf16 v[48:51], v[208:211], v[64:67], v[52:55]
	v_mfma_f32_16x16x32_bf16 v[36:39], v[200:203], v[72:75], v[36:39]
	v_mfma_f32_16x16x32_bf16 v[32:35], v[208:211], v[72:75], v[32:35]
	v_mfma_f32_16x16x32_bf16 v[20:23], v[200:203], v[176:179], v[20:23]
	v_mfma_f32_16x16x32_bf16 v[16:19], v[208:211], v[176:179], v[16:19]
	v_mfma_f32_16x16x32_bf16 v[4:7], v[200:203], v[184:187], v[4:7]
	v_mfma_f32_16x16x32_bf16 v[0:3], v[208:211], v[184:187], v[0:3]
	v_mfma_f32_16x16x32_bf16 v[80:83], v[212:215], v[68:71], v[48:51]
	v_mfma_f32_16x16x32_bf16 v[36:39], v[204:207], v[76:79], v[36:39]
	v_mfma_f32_16x16x32_bf16 v[32:35], v[212:215], v[76:79], v[32:35]
	v_mfma_f32_16x16x32_bf16 v[20:23], v[204:207], v[180:183], v[20:23]
	v_mfma_f32_16x16x32_bf16 v[16:19], v[212:215], v[180:183], v[16:19]
	v_mfma_f32_16x16x32_bf16 v[4:7], v[204:207], v[188:191], v[4:7]
	v_mfma_f32_16x16x32_bf16 v[0:3], v[212:215], v[188:191], v[0:3]
	s_add_i32 s66, s66, 2
	s_add_u32 s4, s4, 0x100
	s_addc_u32 s5, s5, 0
	s_add_u32 s45, s45, 0x100
	s_addc_u32 s47, s47, 0
	s_cmpk_gt_u32 s66, 0x7d
	s_barrier
